# load segments of all six GEMM K-loops made VALU-free (B-fragment LDS addresses via one persistent VGPR + immediate offsets, remaining LDS-DMA in saddr form with a scalar a2+kstep base); no s_setprio
# speedup vs baseline: 1.0161x; 1.0035x over previous
.LBB0_145:
	s_ashr_i32 s13, s12, 31
	s_lshl_b64 s[14:15], s[12:13], 20
	s_add_u32 s14, s10, s14
	s_addc_u32 s15, s11, s15
	s_and_b64 s[22:23], s[38:39], exec
	s_cselect_b32 s13, s15, s41
	s_cselect_b32 s56, s14, s40
	s_ashr_i32 s9, s8, 31
	s_lshl_b64 s[22:23], s[8:9], 20
	s_add_u32 s22, s44, s22
	s_addc_u32 s23, s45, s23
	s_and_b64 s[42:43], s[38:39], exec
	s_cselect_b32 s9, s23, s35
	s_cselect_b32 s57, s22, s34
	s_add_u32 s58, s34, 0x10000
	s_addc_u32 s59, s35, 0
	s_add_u32 s34, s40, 0x80080
	v_mov_b32_e32 v4, 0
	s_addc_u32 s35, s41, 0
	s_mov_b32 s60, -2
	v_mov_b32_e32 v5, v4
	v_mov_b32_e32 v6, v4
	v_mov_b32_e32 v7, v4
	v_mov_b32_e32 v12, v4
	v_mov_b32_e32 v13, v4
	v_mov_b32_e32 v14, v4
	v_mov_b32_e32 v15, v4
	v_mov_b32_e32 v20, v4
	v_mov_b32_e32 v21, v4
	v_mov_b32_e32 v22, v4
	v_mov_b32_e32 v23, v4
	v_mov_b32_e32 v28, v4
	v_mov_b32_e32 v29, v4
	v_mov_b32_e32 v30, v4
	v_mov_b32_e32 v31, v4
	v_mov_b32_e32 v36, v4
	v_mov_b32_e32 v37, v4
	v_mov_b32_e32 v38, v4
	v_mov_b32_e32 v39, v4
	v_mov_b32_e32 v44, v4
	v_mov_b32_e32 v45, v4
	v_mov_b32_e32 v46, v4
	v_mov_b32_e32 v47, v4
	v_mov_b32_e32 v52, v4
	v_mov_b32_e32 v53, v4
	v_mov_b32_e32 v54, v4
	v_mov_b32_e32 v55, v4
	v_mov_b32_e32 v60, v4
	v_mov_b32_e32 v61, v4
	v_mov_b32_e32 v62, v4
	v_mov_b32_e32 v63, v4
	v_mov_b32_e32 v8, v4
	v_mov_b32_e32 v9, v4
	v_mov_b32_e32 v10, v4
	v_mov_b32_e32 v11, v4
	v_mov_b32_e32 v16, v4
	v_mov_b32_e32 v17, v4
	v_mov_b32_e32 v18, v4
	v_mov_b32_e32 v19, v4
	v_mov_b32_e32 v24, v4
	v_mov_b32_e32 v25, v4
	v_mov_b32_e32 v26, v4
	v_mov_b32_e32 v27, v4
	v_mov_b32_e32 v32, v4
	v_mov_b32_e32 v33, v4
	v_mov_b32_e32 v34, v4
	v_mov_b32_e32 v35, v4
	v_mov_b32_e32 v40, v4
	v_mov_b32_e32 v41, v4
	v_mov_b32_e32 v42, v4
	v_mov_b32_e32 v43, v4
	v_mov_b32_e32 v48, v4
	v_mov_b32_e32 v49, v4
	v_mov_b32_e32 v50, v4
	v_mov_b32_e32 v51, v4
	v_mov_b32_e32 v56, v4
	v_mov_b32_e32 v57, v4
	v_mov_b32_e32 v58, v4
	v_mov_b32_e32 v59, v4
	v_mov_b32_e32 v64, v4
	v_mov_b32_e32 v65, v4
	v_mov_b32_e32 v66, v4
	v_mov_b32_e32 v67, v4
	v_mov_b32_e32 v68, v4
	v_mov_b32_e32 v69, v4
	v_mov_b32_e32 v70, v4
	v_mov_b32_e32 v71, v4
	v_mov_b32_e32 v76, v4
	v_mov_b32_e32 v77, v4
	v_mov_b32_e32 v78, v4
	v_mov_b32_e32 v79, v4
	v_mov_b32_e32 v84, v4
	v_mov_b32_e32 v85, v4
	v_mov_b32_e32 v86, v4
	v_mov_b32_e32 v87, v4
	v_mov_b32_e32 v92, v4
	v_mov_b32_e32 v93, v4
	v_mov_b32_e32 v94, v4
	v_mov_b32_e32 v95, v4
	v_mov_b32_e32 v100, v4
	v_mov_b32_e32 v101, v4
	v_mov_b32_e32 v102, v4
	v_mov_b32_e32 v103, v4
	v_mov_b32_e32 v108, v4
	v_mov_b32_e32 v109, v4
	v_mov_b32_e32 v110, v4
	v_mov_b32_e32 v111, v4
	v_mov_b32_e32 v116, v4
	v_mov_b32_e32 v117, v4
	v_mov_b32_e32 v118, v4
	v_mov_b32_e32 v119, v4
	v_mov_b32_e32 v124, v4
	v_mov_b32_e32 v125, v4
	v_mov_b32_e32 v126, v4
	v_mov_b32_e32 v127, v4
	v_mov_b32_e32 v72, v4
	v_mov_b32_e32 v73, v4
	v_mov_b32_e32 v74, v4
	v_mov_b32_e32 v75, v4
	v_mov_b32_e32 v80, v4
	v_mov_b32_e32 v81, v4
	v_mov_b32_e32 v82, v4
	v_mov_b32_e32 v83, v4
	v_mov_b32_e32 v88, v4
	v_mov_b32_e32 v89, v4
	v_mov_b32_e32 v90, v4
	v_mov_b32_e32 v91, v4
	v_mov_b32_e32 v96, v4
	v_mov_b32_e32 v97, v4
	v_mov_b32_e32 v98, v4
	v_mov_b32_e32 v99, v4
	v_mov_b32_e32 v104, v4
	v_mov_b32_e32 v105, v4
	v_mov_b32_e32 v106, v4
	v_mov_b32_e32 v107, v4
	v_mov_b32_e32 v112, v4
	v_mov_b32_e32 v113, v4
	v_mov_b32_e32 v114, v4
	v_mov_b32_e32 v115, v4
	v_mov_b32_e32 v120, v4
	v_mov_b32_e32 v121, v4
	v_mov_b32_e32 v122, v4
	v_mov_b32_e32 v123, v4
	v_mov_b32_e32 v128, v4
	v_mov_b32_e32 v129, v4
	v_mov_b32_e32 v130, v4
	v_mov_b32_e32 v131, v4
	v_add_u32_e32 v228, 0x10000, v143
.LBB0_146:
	s_add_u32 s40, s34, 0xfff80080
	s_addc_u32 s41, s35, -1
	s_add_i32 s61, 0, 0x10000
	s_cmp_eq_u32 s60, 28
	s_cselect_b32 s43, s13, s41
	s_cselect_b32 s42, s56, s40
	s_cselect_b32 s41, s9, s59
	s_cselect_b32 s40, s57, s58
	s_add_i32 s64, 0, 0x14000
	ds_read_b128 v[148:151], v228
	ds_read_b128 v[152:155], v228 offset:1024
	ds_read_b128 v[156:159], v228 offset:2048
	ds_read_b128 v[160:163], v228 offset:3072
	ds_read_b128 v[164:167], v228 offset:16384
	ds_read_b128 v[168:171], v228 offset:17408
	ds_read_b128 v[172:175], v228 offset:18432
	ds_read_b128 v[176:179], v228 offset:19456
	s_add_i32 m0, s47, 0xc000
	ds_read_b128 v[180:183], v147
	ds_read_b128 v[184:187], v147 offset:1024
	ds_read_b128 v[188:191], v147 offset:2048
	ds_read_b128 v[192:195], v147 offset:3072
	ds_read_b128 v[202:205], v147 offset:4096
	ds_read_b128 v[214:217], v147 offset:5120
	ds_read_b128 v[218:221], v147 offset:6144
	ds_read_b128 v[222:225], v147 offset:7168
	global_load_lds_dwordx4 v138, s[34:35]
	s_add_i32 m0, s47, 0xe000
	s_nop 0
	global_load_lds_dwordx4 v140, s[34:35]
	s_waitcnt vmcnt(8)
	s_waitcnt lgkmcnt(0)
	s_barrier
	s_waitcnt lgkmcnt(0)
	v_mfma_f32_16x16x32_bf16 v[128:131], v[148:151], v[180:183], v[128:131]
	v_mfma_f32_16x16x32_bf16 v[120:123], v[156:159], v[180:183], v[120:123]
	v_mfma_f32_16x16x32_bf16 v[112:115], v[148:151], v[188:191], v[112:115]
	v_mfma_f32_16x16x32_bf16 v[104:107], v[156:159], v[188:191], v[104:107]
	v_mfma_f32_16x16x32_bf16 v[96:99], v[148:151], v[202:205], v[96:99]
	v_mfma_f32_16x16x32_bf16 v[88:91], v[156:159], v[202:205], v[88:91]
	v_mfma_f32_16x16x32_bf16 v[80:83], v[148:151], v[218:221], v[80:83]
	v_mfma_f32_16x16x32_bf16 v[72:75], v[156:159], v[218:221], v[72:75]
	v_mfma_f32_16x16x32_bf16 v[128:131], v[152:155], v[184:187], v[128:131]
	v_mfma_f32_16x16x32_bf16 v[120:123], v[160:163], v[184:187], v[120:123]
	v_mfma_f32_16x16x32_bf16 v[112:115], v[152:155], v[192:195], v[112:115]
	v_mfma_f32_16x16x32_bf16 v[104:107], v[160:163], v[192:195], v[104:107]
	v_mfma_f32_16x16x32_bf16 v[96:99], v[152:155], v[214:217], v[96:99]
	v_mfma_f32_16x16x32_bf16 v[88:91], v[160:163], v[214:217], v[88:91]
	v_mfma_f32_16x16x32_bf16 v[80:83], v[152:155], v[222:225], v[80:83]
	v_mfma_f32_16x16x32_bf16 v[72:75], v[160:163], v[222:225], v[72:75]
	v_mfma_f32_16x16x32_bf16 v[124:127], v[164:167], v[180:183], v[124:127]
	v_mfma_f32_16x16x32_bf16 v[116:119], v[172:175], v[180:183], v[116:119]
	v_mfma_f32_16x16x32_bf16 v[108:111], v[164:167], v[188:191], v[108:111]
	v_mfma_f32_16x16x32_bf16 v[100:103], v[172:175], v[188:191], v[100:103]
	v_mfma_f32_16x16x32_bf16 v[92:95], v[164:167], v[202:205], v[92:95]
	v_mfma_f32_16x16x32_bf16 v[84:87], v[172:175], v[202:205], v[84:87]
	v_mfma_f32_16x16x32_bf16 v[76:79], v[164:167], v[218:221], v[76:79]
	v_mfma_f32_16x16x32_bf16 v[68:71], v[172:175], v[218:221], v[68:71]
	v_mfma_f32_16x16x32_bf16 v[124:127], v[168:171], v[184:187], v[124:127]
	v_mfma_f32_16x16x32_bf16 v[116:119], v[176:179], v[184:187], v[116:119]
	v_mfma_f32_16x16x32_bf16 v[108:111], v[168:171], v[192:195], v[108:111]
	v_mfma_f32_16x16x32_bf16 v[100:103], v[176:179], v[192:195], v[100:103]
	v_mfma_f32_16x16x32_bf16 v[92:95], v[168:171], v[214:217], v[92:95]
	v_mfma_f32_16x16x32_bf16 v[84:87], v[176:179], v[214:217], v[84:87]
	v_mfma_f32_16x16x32_bf16 v[76:79], v[168:171], v[222:225], v[76:79]
	v_mfma_f32_16x16x32_bf16 v[68:71], v[176:179], v[222:225], v[68:71]
	s_barrier
	s_add_u32 s98, s42, s4
	s_addc_u32 s99, s43, s5
	s_add_i32 s61, s61, s46
	s_mov_b32 m0, s61
	ds_read_b128 v[180:183], v147 offset:16384
	ds_read_b128 v[184:187], v147 offset:17408
	ds_read_b128 v[188:191], v147 offset:18432
	ds_read_b128 v[192:195], v147 offset:19456
	ds_read_b128 v[202:205], v147 offset:20480
	ds_read_b128 v[214:217], v147 offset:21504
	ds_read_b128 v[218:221], v147 offset:22528
	ds_read_b128 v[222:225], v147 offset:23552
	global_load_lds_dwordx4 v2, s[40:41]
	s_add_i32 m0, s61, 0x2000
	s_add_u32 s62, s40, 0x4000
	s_addc_u32 s63, s41, 0
	s_add_i32 s61, s64, s46
	global_load_lds_dwordx4 v132, s[40:41]
	s_mov_b32 m0, s61
	s_nop 0
	global_load_lds_dwordx4 v2, s[62:63]
	s_add_i32 m0, s61, 0x2000
	s_nop 0
	global_load_lds_dwordx4 v132, s[62:63]
	s_mov_b32 m0, s47
	s_nop 0
	global_load_lds_dwordx4 v136, s[42:43]
	s_mov_b32 m0, s48
	s_nop 0
	global_load_lds_dwordx4 v134, s[42:43]
	s_waitcnt vmcnt(8)
	s_waitcnt lgkmcnt(0)
	s_barrier
	s_waitcnt lgkmcnt(0)
	v_mfma_f32_16x16x32_bf16 v[64:67], v[148:151], v[180:183], v[64:67]
	v_mfma_f32_16x16x32_bf16 v[56:59], v[156:159], v[180:183], v[56:59]
	v_mfma_f32_16x16x32_bf16 v[48:51], v[148:151], v[188:191], v[48:51]
	v_mfma_f32_16x16x32_bf16 v[40:43], v[156:159], v[188:191], v[40:43]
	v_mfma_f32_16x16x32_bf16 v[32:35], v[148:151], v[202:205], v[32:35]
	v_mfma_f32_16x16x32_bf16 v[24:27], v[156:159], v[202:205], v[24:27]
	v_mfma_f32_16x16x32_bf16 v[16:19], v[148:151], v[218:221], v[16:19]
	v_mfma_f32_16x16x32_bf16 v[8:11], v[156:159], v[218:221], v[8:11]
	v_mfma_f32_16x16x32_bf16 v[64:67], v[152:155], v[184:187], v[64:67]
	v_mfma_f32_16x16x32_bf16 v[56:59], v[160:163], v[184:187], v[56:59]
	v_mfma_f32_16x16x32_bf16 v[48:51], v[152:155], v[192:195], v[48:51]
	v_mfma_f32_16x16x32_bf16 v[40:43], v[160:163], v[192:195], v[40:43]
	v_mfma_f32_16x16x32_bf16 v[32:35], v[152:155], v[214:217], v[32:35]
	v_mfma_f32_16x16x32_bf16 v[24:27], v[160:163], v[214:217], v[24:27]
	v_mfma_f32_16x16x32_bf16 v[16:19], v[152:155], v[222:225], v[16:19]
	v_mfma_f32_16x16x32_bf16 v[8:11], v[160:163], v[222:225], v[8:11]
	v_mfma_f32_16x16x32_bf16 v[60:63], v[164:167], v[180:183], v[60:63]
	v_mfma_f32_16x16x32_bf16 v[52:55], v[172:175], v[180:183], v[52:55]
	v_mfma_f32_16x16x32_bf16 v[44:47], v[164:167], v[188:191], v[44:47]
	v_mfma_f32_16x16x32_bf16 v[36:39], v[172:175], v[188:191], v[36:39]
	v_mfma_f32_16x16x32_bf16 v[28:31], v[164:167], v[202:205], v[28:31]
	v_mfma_f32_16x16x32_bf16 v[20:23], v[172:175], v[202:205], v[20:23]
	v_mfma_f32_16x16x32_bf16 v[12:15], v[164:167], v[218:221], v[12:15]
	v_mfma_f32_16x16x32_bf16 v[4:7], v[172:175], v[218:221], v[4:7]
	v_mfma_f32_16x16x32_bf16 v[60:63], v[168:171], v[184:187], v[60:63]
	v_mfma_f32_16x16x32_bf16 v[52:55], v[176:179], v[184:187], v[52:55]
	v_mfma_f32_16x16x32_bf16 v[44:47], v[168:171], v[192:195], v[44:47]
	v_mfma_f32_16x16x32_bf16 v[36:39], v[176:179], v[192:195], v[36:39]
	v_mfma_f32_16x16x32_bf16 v[28:31], v[168:171], v[214:217], v[28:31]
	v_mfma_f32_16x16x32_bf16 v[20:23], v[176:179], v[214:217], v[20:23]
	v_mfma_f32_16x16x32_bf16 v[12:15], v[168:171], v[222:225], v[12:15]
	v_mfma_f32_16x16x32_bf16 v[4:7], v[176:179], v[222:225], v[4:7]
	s_barrier
	s_add_i32 s61, 0, 0x18000
	s_add_i32 s62, 0, 0x1c000
	ds_read_b128 v[148:151], v228 offset:32768
	ds_read_b128 v[152:155], v228 offset:33792
	ds_read_b128 v[156:159], v228 offset:34816
	ds_read_b128 v[160:163], v228 offset:35840
	ds_read_b128 v[164:167], v228 offset:49152
	ds_read_b128 v[168:171], v228 offset:50176
	ds_read_b128 v[172:175], v228 offset:51200
	ds_read_b128 v[176:179], v228 offset:52224
	s_add_u32 s42, s42, 0x80000
	s_addc_u32 s43, s43, 0
	s_mov_b32 m0, s49
	ds_read_b128 v[180:183], v147 offset:32768
	ds_read_b128 v[184:187], v147 offset:33792
	ds_read_b128 v[188:191], v147 offset:34816
	ds_read_b128 v[192:195], v147 offset:35840
	ds_read_b128 v[202:205], v147 offset:36864
	ds_read_b128 v[214:217], v147 offset:37888
	ds_read_b128 v[218:221], v147 offset:38912
	ds_read_b128 v[222:225], v147 offset:39936
	global_load_lds_dwordx4 v136, s[42:43]
	s_mov_b32 m0, s50
	s_nop 0
	global_load_lds_dwordx4 v134, s[42:43]
	s_waitcnt vmcnt(8)
	s_waitcnt lgkmcnt(0)
	s_barrier
	s_waitcnt lgkmcnt(0)
	v_mfma_f32_16x16x32_bf16 v[128:131], v[148:151], v[180:183], v[128:131]
	v_mfma_f32_16x16x32_bf16 v[120:123], v[156:159], v[180:183], v[120:123]
	v_mfma_f32_16x16x32_bf16 v[112:115], v[148:151], v[188:191], v[112:115]
	v_mfma_f32_16x16x32_bf16 v[104:107], v[156:159], v[188:191], v[104:107]
	v_mfma_f32_16x16x32_bf16 v[96:99], v[148:151], v[202:205], v[96:99]
	v_mfma_f32_16x16x32_bf16 v[88:91], v[156:159], v[202:205], v[88:91]
	v_mfma_f32_16x16x32_bf16 v[80:83], v[148:151], v[218:221], v[80:83]
	v_mfma_f32_16x16x32_bf16 v[72:75], v[156:159], v[218:221], v[72:75]
	v_mfma_f32_16x16x32_bf16 v[128:131], v[152:155], v[184:187], v[128:131]
	v_mfma_f32_16x16x32_bf16 v[120:123], v[160:163], v[184:187], v[120:123]
	v_mfma_f32_16x16x32_bf16 v[112:115], v[152:155], v[192:195], v[112:115]
	v_mfma_f32_16x16x32_bf16 v[104:107], v[160:163], v[192:195], v[104:107]
	v_mfma_f32_16x16x32_bf16 v[96:99], v[152:155], v[214:217], v[96:99]
	v_mfma_f32_16x16x32_bf16 v[88:91], v[160:163], v[214:217], v[88:91]
	v_mfma_f32_16x16x32_bf16 v[80:83], v[152:155], v[222:225], v[80:83]
	v_mfma_f32_16x16x32_bf16 v[72:75], v[160:163], v[222:225], v[72:75]
	v_mfma_f32_16x16x32_bf16 v[124:127], v[164:167], v[180:183], v[124:127]
	v_mfma_f32_16x16x32_bf16 v[116:119], v[172:175], v[180:183], v[116:119]
	v_mfma_f32_16x16x32_bf16 v[108:111], v[164:167], v[188:191], v[108:111]
	v_mfma_f32_16x16x32_bf16 v[100:103], v[172:175], v[188:191], v[100:103]
	v_mfma_f32_16x16x32_bf16 v[92:95], v[164:167], v[202:205], v[92:95]
	v_mfma_f32_16x16x32_bf16 v[84:87], v[172:175], v[202:205], v[84:87]
	v_mfma_f32_16x16x32_bf16 v[76:79], v[164:167], v[218:221], v[76:79]
	v_mfma_f32_16x16x32_bf16 v[68:71], v[172:175], v[218:221], v[68:71]
	v_mfma_f32_16x16x32_bf16 v[124:127], v[168:171], v[184:187], v[124:127]
	v_mfma_f32_16x16x32_bf16 v[116:119], v[176:179], v[184:187], v[116:119]
	v_mfma_f32_16x16x32_bf16 v[108:111], v[168:171], v[192:195], v[108:111]
	v_mfma_f32_16x16x32_bf16 v[100:103], v[176:179], v[192:195], v[100:103]
	v_mfma_f32_16x16x32_bf16 v[92:95], v[168:171], v[214:217], v[92:95]
	v_mfma_f32_16x16x32_bf16 v[84:87], v[176:179], v[214:217], v[84:87]
	v_mfma_f32_16x16x32_bf16 v[76:79], v[168:171], v[222:225], v[76:79]
	v_mfma_f32_16x16x32_bf16 v[68:71], v[176:179], v[222:225], v[68:71]
	s_barrier
	s_add_u32 s42, s40, 0x8000
	s_addc_u32 s43, s41, 0
	s_add_i32 s61, s61, s46
	s_mov_b32 m0, s61
	ds_read_b128 v[180:183], v147 offset:49152
	ds_read_b128 v[184:187], v147 offset:50176
	ds_read_b128 v[188:191], v147 offset:51200
	ds_read_b128 v[192:195], v147 offset:52224
	ds_read_b128 v[202:205], v147 offset:53248
	ds_read_b128 v[214:217], v147 offset:54272
	ds_read_b128 v[218:221], v147 offset:55296
	ds_read_b128 v[222:225], v147 offset:56320
	global_load_lds_dwordx4 v2, s[42:43]
	s_add_i32 m0, s61, 0x2000
	s_add_u32 s40, s40, 0xc000
	s_addc_u32 s41, s41, 0
	global_load_lds_dwordx4 v132, s[42:43]
	s_add_i32 s42, s62, s46
	s_mov_b32 m0, s42
	s_nop 0
	global_load_lds_dwordx4 v2, s[40:41]
	s_add_i32 m0, s42, 0x2000
	s_nop 0
	global_load_lds_dwordx4 v132, s[40:41]
	s_mov_b32 m0, s51
	s_nop 0
	global_load_lds_dwordx4 v136, s[98:99]
	s_mov_b32 m0, s52
	s_nop 0
	global_load_lds_dwordx4 v134, s[98:99]
	s_waitcnt vmcnt(8)
	s_waitcnt lgkmcnt(0)
	s_barrier
	s_waitcnt lgkmcnt(0)
	v_mfma_f32_16x16x32_bf16 v[64:67], v[148:151], v[180:183], v[64:67]
	v_mfma_f32_16x16x32_bf16 v[56:59], v[156:159], v[180:183], v[56:59]
	v_mfma_f32_16x16x32_bf16 v[48:51], v[148:151], v[188:191], v[48:51]
	v_mfma_f32_16x16x32_bf16 v[40:43], v[156:159], v[188:191], v[40:43]
	v_mfma_f32_16x16x32_bf16 v[32:35], v[148:151], v[202:205], v[32:35]
	v_mfma_f32_16x16x32_bf16 v[24:27], v[156:159], v[202:205], v[24:27]
	v_mfma_f32_16x16x32_bf16 v[16:19], v[148:151], v[218:221], v[16:19]
	v_mfma_f32_16x16x32_bf16 v[8:11], v[156:159], v[218:221], v[8:11]
	v_mfma_f32_16x16x32_bf16 v[64:67], v[152:155], v[184:187], v[64:67]
	v_mfma_f32_16x16x32_bf16 v[56:59], v[160:163], v[184:187], v[56:59]
	v_mfma_f32_16x16x32_bf16 v[48:51], v[152:155], v[192:195], v[48:51]
	v_mfma_f32_16x16x32_bf16 v[40:43], v[160:163], v[192:195], v[40:43]
	v_mfma_f32_16x16x32_bf16 v[32:35], v[152:155], v[214:217], v[32:35]
	v_mfma_f32_16x16x32_bf16 v[24:27], v[160:163], v[214:217], v[24:27]
	v_mfma_f32_16x16x32_bf16 v[16:19], v[152:155], v[222:225], v[16:19]
	v_mfma_f32_16x16x32_bf16 v[8:11], v[160:163], v[222:225], v[8:11]
	v_mfma_f32_16x16x32_bf16 v[60:63], v[164:167], v[180:183], v[60:63]
	v_mfma_f32_16x16x32_bf16 v[52:55], v[172:175], v[180:183], v[52:55]
	v_mfma_f32_16x16x32_bf16 v[44:47], v[164:167], v[188:191], v[44:47]
	v_mfma_f32_16x16x32_bf16 v[36:39], v[172:175], v[188:191], v[36:39]
	v_mfma_f32_16x16x32_bf16 v[28:31], v[164:167], v[202:205], v[28:31]
	v_mfma_f32_16x16x32_bf16 v[20:23], v[172:175], v[202:205], v[20:23]
	v_mfma_f32_16x16x32_bf16 v[12:15], v[164:167], v[218:221], v[12:15]
	v_mfma_f32_16x16x32_bf16 v[4:7], v[172:175], v[218:221], v[4:7]
	v_mfma_f32_16x16x32_bf16 v[60:63], v[168:171], v[184:187], v[60:63]
	v_mfma_f32_16x16x32_bf16 v[52:55], v[176:179], v[184:187], v[52:55]
	v_mfma_f32_16x16x32_bf16 v[44:47], v[168:171], v[192:195], v[44:47]
	v_mfma_f32_16x16x32_bf16 v[36:39], v[176:179], v[192:195], v[36:39]
	v_mfma_f32_16x16x32_bf16 v[28:31], v[168:171], v[214:217], v[28:31]
	v_mfma_f32_16x16x32_bf16 v[20:23], v[176:179], v[214:217], v[20:23]
	v_mfma_f32_16x16x32_bf16 v[12:15], v[168:171], v[222:225], v[12:15]
	v_mfma_f32_16x16x32_bf16 v[4:7], v[176:179], v[222:225], v[4:7]
	s_barrier
	s_add_i32 s60, s60, 2
	s_add_u32 s58, s58, 0x10000
	s_addc_u32 s59, s59, 0
	s_add_u32 s34, s34, 0x100
	s_addc_u32 s35, s35, 0
	s_cmp_gt_u32 s60, 29
	s_cbranch_scc0 .LBB0_146
	s_and_b64 vcc, exec, s[6:7]
	s_cbranch_vccz .LBB0_149
	s_barrier

.LBB0_222:
	s_add_u32 s64, s22, 0x10000
	v_mov_b32_e32 v4, 0
	s_addc_u32 s65, s23, 0
	s_mov_b32 s66, -2
	v_mov_b32_e32 v5, v4
	v_mov_b32_e32 v6, v4
	v_mov_b32_e32 v7, v4
	v_mov_b32_e32 v8, v4
	v_mov_b32_e32 v9, v4
	v_mov_b32_e32 v10, v4
	v_mov_b32_e32 v11, v4
	v_mov_b32_e32 v20, v4
	v_mov_b32_e32 v21, v4
	v_mov_b32_e32 v22, v4
	v_mov_b32_e32 v23, v4
	v_mov_b32_e32 v24, v4
	v_mov_b32_e32 v25, v4
	v_mov_b32_e32 v26, v4
	v_mov_b32_e32 v27, v4
	v_mov_b32_e32 v36, v4
	v_mov_b32_e32 v37, v4
	v_mov_b32_e32 v38, v4
	v_mov_b32_e32 v39, v4
	v_mov_b32_e32 v40, v4
	v_mov_b32_e32 v41, v4
	v_mov_b32_e32 v42, v4
	v_mov_b32_e32 v43, v4
	v_mov_b32_e32 v52, v4
	v_mov_b32_e32 v53, v4
	v_mov_b32_e32 v54, v4
	v_mov_b32_e32 v55, v4
	v_mov_b32_e32 v56, v4
	v_mov_b32_e32 v57, v4
	v_mov_b32_e32 v58, v4
	v_mov_b32_e32 v59, v4
	v_mov_b32_e32 v12, v4
	v_mov_b32_e32 v13, v4
	v_mov_b32_e32 v14, v4
	v_mov_b32_e32 v15, v4
	v_mov_b32_e32 v16, v4
	v_mov_b32_e32 v17, v4
	v_mov_b32_e32 v18, v4
	v_mov_b32_e32 v19, v4
	v_mov_b32_e32 v28, v4
	v_mov_b32_e32 v29, v4
	v_mov_b32_e32 v30, v4
	v_mov_b32_e32 v31, v4
	v_mov_b32_e32 v32, v4
	v_mov_b32_e32 v33, v4
	v_mov_b32_e32 v34, v4
	v_mov_b32_e32 v35, v4
	v_mov_b32_e32 v44, v4
	v_mov_b32_e32 v45, v4
	v_mov_b32_e32 v46, v4
	v_mov_b32_e32 v47, v4
	v_mov_b32_e32 v48, v4
	v_mov_b32_e32 v49, v4
	v_mov_b32_e32 v50, v4
	v_mov_b32_e32 v51, v4
	v_mov_b32_e32 v60, v4
	v_mov_b32_e32 v61, v4
	v_mov_b32_e32 v62, v4
	v_mov_b32_e32 v63, v4
	v_mov_b32_e32 v64, v4
	v_mov_b32_e32 v65, v4
	v_mov_b32_e32 v66, v4
	v_mov_b32_e32 v67, v4
	v_mov_b32_e32 v68, v4
	v_mov_b32_e32 v69, v4
	v_mov_b32_e32 v70, v4
	v_mov_b32_e32 v71, v4
	v_mov_b32_e32 v72, v4
	v_mov_b32_e32 v73, v4
	v_mov_b32_e32 v74, v4
	v_mov_b32_e32 v75, v4
	v_mov_b32_e32 v84, v4
	v_mov_b32_e32 v85, v4
	v_mov_b32_e32 v86, v4
	v_mov_b32_e32 v87, v4
	v_mov_b32_e32 v88, v4
	v_mov_b32_e32 v89, v4
	v_mov_b32_e32 v90, v4
	v_mov_b32_e32 v91, v4
	v_mov_b32_e32 v100, v4
	v_mov_b32_e32 v101, v4
	v_mov_b32_e32 v102, v4
	v_mov_b32_e32 v103, v4
	v_mov_b32_e32 v104, v4
	v_mov_b32_e32 v105, v4
	v_mov_b32_e32 v106, v4
	v_mov_b32_e32 v107, v4
	v_mov_b32_e32 v124, v4
	v_mov_b32_e32 v125, v4
	v_mov_b32_e32 v126, v4
	v_mov_b32_e32 v127, v4
	v_mov_b32_e32 v132, v4
	v_mov_b32_e32 v133, v4
	v_mov_b32_e32 v134, v4
	v_mov_b32_e32 v135, v4
	v_mov_b32_e32 v76, v4
	v_mov_b32_e32 v77, v4
	v_mov_b32_e32 v78, v4
	v_mov_b32_e32 v79, v4
	v_mov_b32_e32 v80, v4
	v_mov_b32_e32 v81, v4
	v_mov_b32_e32 v82, v4
	v_mov_b32_e32 v83, v4
	v_mov_b32_e32 v92, v4
	v_mov_b32_e32 v93, v4
	v_mov_b32_e32 v94, v4
	v_mov_b32_e32 v95, v4
	v_mov_b32_e32 v96, v4
	v_mov_b32_e32 v97, v4
	v_mov_b32_e32 v98, v4
	v_mov_b32_e32 v99, v4
	v_mov_b32_e32 v112, v4
	v_mov_b32_e32 v113, v4
	v_mov_b32_e32 v114, v4
	v_mov_b32_e32 v115, v4
	v_mov_b32_e32 v120, v4
	v_mov_b32_e32 v121, v4
	v_mov_b32_e32 v122, v4
	v_mov_b32_e32 v123, v4
	v_mov_b32_e32 v152, v4
	v_mov_b32_e32 v153, v4
	v_mov_b32_e32 v154, v4
	v_mov_b32_e32 v155, v4
	v_mov_b32_e32 v160, v4
	v_mov_b32_e32 v161, v4
	v_mov_b32_e32 v162, v4
	v_mov_b32_e32 v163, v4
	v_add_u32_e32 v226, 0x10000, v202
.LBB0_223:
	s_add_u32 s22, s14, 0x100
	s_addc_u32 s23, s15, 0
	s_add_i32 s67, 0, 0x10000
	s_cmpk_eq_i32 s66, 0x54
	s_cselect_b32 s49, s9, s23
	s_cselect_b32 s48, s8, s22
	s_cselect_b32 s35, s13, s65
	s_cselect_b32 s34, s12, s64
	s_add_i32 s68, 0, 0x14000
	ds_read_b128 v[108:111], v226
	ds_read_b128 v[116:119], v226 offset:1024
	ds_read_b128 v[128:131], v226 offset:2048
	ds_read_b128 v[136:139], v226 offset:3072
	ds_read_b128 v[140:143], v226 offset:16384
	ds_read_b128 v[144:147], v226 offset:17408
	ds_read_b128 v[148:151], v226 offset:18432
	ds_read_b128 v[156:159], v226 offset:19456
	s_add_i32 m0, s53, 0xc000
	ds_read_b128 v[164:167], v204
	ds_read_b128 v[168:171], v204 offset:1024
	ds_read_b128 v[172:175], v204 offset:2048
	ds_read_b128 v[176:179], v204 offset:3072
	ds_read_b128 v[180:183], v204 offset:4096
	ds_read_b128 v[184:187], v204 offset:5120
	ds_read_b128 v[188:191], v204 offset:6144
	ds_read_b128 v[192:195], v204 offset:7168
	global_load_lds_dwordx4 v220, s[14:15]
	s_add_i32 m0, s53, 0xe000
	s_nop 0
	global_load_lds_dwordx4 v222, s[14:15]
	s_waitcnt vmcnt(8)
	s_waitcnt lgkmcnt(0)
	s_barrier
	s_waitcnt lgkmcnt(0)
	v_mfma_f32_16x16x32_bf16 v[160:163], v[108:111], v[164:167], v[160:163]
	v_mfma_f32_16x16x32_bf16 v[152:155], v[128:131], v[164:167], v[152:155]
	v_mfma_f32_16x16x32_bf16 v[120:123], v[108:111], v[172:175], v[120:123]
	v_mfma_f32_16x16x32_bf16 v[112:115], v[128:131], v[172:175], v[112:115]
	v_mfma_f32_16x16x32_bf16 v[96:99], v[108:111], v[180:183], v[96:99]
	v_mfma_f32_16x16x32_bf16 v[92:95], v[128:131], v[180:183], v[92:95]
	v_mfma_f32_16x16x32_bf16 v[80:83], v[108:111], v[188:191], v[80:83]
	v_mfma_f32_16x16x32_bf16 v[76:79], v[128:131], v[188:191], v[76:79]
	v_mfma_f32_16x16x32_bf16 v[160:163], v[116:119], v[168:171], v[160:163]
	v_mfma_f32_16x16x32_bf16 v[152:155], v[136:139], v[168:171], v[152:155]
	v_mfma_f32_16x16x32_bf16 v[120:123], v[116:119], v[176:179], v[120:123]
	v_mfma_f32_16x16x32_bf16 v[112:115], v[136:139], v[176:179], v[112:115]
	v_mfma_f32_16x16x32_bf16 v[96:99], v[116:119], v[184:187], v[96:99]
	v_mfma_f32_16x16x32_bf16 v[92:95], v[136:139], v[184:187], v[92:95]
	v_mfma_f32_16x16x32_bf16 v[80:83], v[116:119], v[192:195], v[80:83]
	v_mfma_f32_16x16x32_bf16 v[76:79], v[136:139], v[192:195], v[76:79]
	v_mfma_f32_16x16x32_bf16 v[132:135], v[140:143], v[164:167], v[132:135]
	v_mfma_f32_16x16x32_bf16 v[124:127], v[148:151], v[164:167], v[124:127]
	v_mfma_f32_16x16x32_bf16 v[104:107], v[140:143], v[172:175], v[104:107]
	v_mfma_f32_16x16x32_bf16 v[100:103], v[148:151], v[172:175], v[100:103]
	v_mfma_f32_16x16x32_bf16 v[88:91], v[140:143], v[180:183], v[88:91]
	v_mfma_f32_16x16x32_bf16 v[84:87], v[148:151], v[180:183], v[84:87]
	v_mfma_f32_16x16x32_bf16 v[72:75], v[140:143], v[188:191], v[72:75]
	v_mfma_f32_16x16x32_bf16 v[68:71], v[148:151], v[188:191], v[68:71]
	v_mfma_f32_16x16x32_bf16 v[132:135], v[144:147], v[168:171], v[132:135]
	v_mfma_f32_16x16x32_bf16 v[124:127], v[156:159], v[168:171], v[124:127]
	v_mfma_f32_16x16x32_bf16 v[104:107], v[144:147], v[176:179], v[104:107]
	v_mfma_f32_16x16x32_bf16 v[100:103], v[156:159], v[176:179], v[100:103]
	v_mfma_f32_16x16x32_bf16 v[88:91], v[144:147], v[184:187], v[88:91]
	v_mfma_f32_16x16x32_bf16 v[84:87], v[156:159], v[184:187], v[84:87]
	v_mfma_f32_16x16x32_bf16 v[72:75], v[144:147], v[192:195], v[72:75]
	v_mfma_f32_16x16x32_bf16 v[68:71], v[156:159], v[192:195], v[68:71]
	s_barrier
	s_add_u32 s98, s48, s4
	s_addc_u32 s99, s49, s5
	s_add_i32 s14, s67, s52
	s_mov_b32 m0, s14
	ds_read_b128 v[164:167], v204 offset:16384
	ds_read_b128 v[168:171], v204 offset:17408
	ds_read_b128 v[172:175], v204 offset:18432
	ds_read_b128 v[176:179], v204 offset:19456
	ds_read_b128 v[180:183], v204 offset:20480
	ds_read_b128 v[184:187], v204 offset:21504
	ds_read_b128 v[188:191], v204 offset:22528
	ds_read_b128 v[192:195], v204 offset:23552
	global_load_lds_dwordx4 v2, s[34:35]
	s_add_i32 m0, s14, 0x2000
	s_add_u32 s14, s34, 0x4000
	s_addc_u32 s15, s35, 0
	s_add_i32 s67, s68, s52
	global_load_lds_dwordx4 v214, s[34:35]
	s_mov_b32 m0, s67
	s_nop 0
	global_load_lds_dwordx4 v2, s[14:15]
	s_add_i32 m0, s67, 0x2000
	s_nop 0
	global_load_lds_dwordx4 v214, s[14:15]
	s_mov_b32 m0, s53
	s_nop 0
	global_load_lds_dwordx4 v218, s[48:49]
	s_mov_b32 m0, s54
	s_nop 0
	global_load_lds_dwordx4 v216, s[48:49]
	s_waitcnt vmcnt(8)
	s_waitcnt lgkmcnt(0)
	s_barrier
	s_waitcnt lgkmcnt(0)
	v_mfma_f32_16x16x32_bf16 v[64:67], v[108:111], v[164:167], v[64:67]
	v_mfma_f32_16x16x32_bf16 v[60:63], v[128:131], v[164:167], v[60:63]
	v_mfma_f32_16x16x32_bf16 v[48:51], v[108:111], v[172:175], v[48:51]
	v_mfma_f32_16x16x32_bf16 v[44:47], v[128:131], v[172:175], v[44:47]
	v_mfma_f32_16x16x32_bf16 v[32:35], v[108:111], v[180:183], v[32:35]
	v_mfma_f32_16x16x32_bf16 v[28:31], v[128:131], v[180:183], v[28:31]
	v_mfma_f32_16x16x32_bf16 v[16:19], v[108:111], v[188:191], v[16:19]
	v_mfma_f32_16x16x32_bf16 v[12:15], v[128:131], v[188:191], v[12:15]
	v_mfma_f32_16x16x32_bf16 v[64:67], v[116:119], v[168:171], v[64:67]
	v_mfma_f32_16x16x32_bf16 v[60:63], v[136:139], v[168:171], v[60:63]
	v_mfma_f32_16x16x32_bf16 v[48:51], v[116:119], v[176:179], v[48:51]
	v_mfma_f32_16x16x32_bf16 v[44:47], v[136:139], v[176:179], v[44:47]
	v_mfma_f32_16x16x32_bf16 v[32:35], v[116:119], v[184:187], v[32:35]
	v_mfma_f32_16x16x32_bf16 v[28:31], v[136:139], v[184:187], v[28:31]
	v_mfma_f32_16x16x32_bf16 v[16:19], v[116:119], v[192:195], v[16:19]
	v_mfma_f32_16x16x32_bf16 v[12:15], v[136:139], v[192:195], v[12:15]
	v_mfma_f32_16x16x32_bf16 v[56:59], v[140:143], v[164:167], v[56:59]
	v_mfma_f32_16x16x32_bf16 v[52:55], v[148:151], v[164:167], v[52:55]
	v_mfma_f32_16x16x32_bf16 v[40:43], v[140:143], v[172:175], v[40:43]
	v_mfma_f32_16x16x32_bf16 v[36:39], v[148:151], v[172:175], v[36:39]
	v_mfma_f32_16x16x32_bf16 v[24:27], v[140:143], v[180:183], v[24:27]
	v_mfma_f32_16x16x32_bf16 v[20:23], v[148:151], v[180:183], v[20:23]
	v_mfma_f32_16x16x32_bf16 v[8:11], v[140:143], v[188:191], v[8:11]
	v_mfma_f32_16x16x32_bf16 v[4:7], v[148:151], v[188:191], v[4:7]
	v_mfma_f32_16x16x32_bf16 v[56:59], v[144:147], v[168:171], v[56:59]
	v_mfma_f32_16x16x32_bf16 v[52:55], v[156:159], v[168:171], v[52:55]
	v_mfma_f32_16x16x32_bf16 v[40:43], v[144:147], v[176:179], v[40:43]
	v_mfma_f32_16x16x32_bf16 v[36:39], v[156:159], v[176:179], v[36:39]
	v_mfma_f32_16x16x32_bf16 v[24:27], v[144:147], v[184:187], v[24:27]
	v_mfma_f32_16x16x32_bf16 v[20:23], v[156:159], v[184:187], v[20:23]
	v_mfma_f32_16x16x32_bf16 v[8:11], v[144:147], v[192:195], v[8:11]
	v_mfma_f32_16x16x32_bf16 v[4:7], v[156:159], v[192:195], v[4:7]
	s_barrier
	s_add_i32 s67, 0, 0x18000
	s_add_i32 s68, 0, 0x1c000
	ds_read_b128 v[108:111], v226 offset:32768
	ds_read_b128 v[116:119], v226 offset:33792
	ds_read_b128 v[128:131], v226 offset:34816
	ds_read_b128 v[136:139], v226 offset:35840
	ds_read_b128 v[140:143], v226 offset:49152
	ds_read_b128 v[144:147], v226 offset:50176
	ds_read_b128 v[148:151], v226 offset:51200
	ds_read_b128 v[156:159], v226 offset:52224
	s_add_u32 s14, s48, 0x160000
	s_addc_u32 s15, s49, 0
	s_mov_b32 m0, s55
	ds_read_b128 v[164:167], v204 offset:32768
	ds_read_b128 v[168:171], v204 offset:33792
	ds_read_b128 v[172:175], v204 offset:34816
	ds_read_b128 v[176:179], v204 offset:35840
	ds_read_b128 v[180:183], v204 offset:36864
	ds_read_b128 v[184:187], v204 offset:37888
	ds_read_b128 v[188:191], v204 offset:38912
	ds_read_b128 v[192:195], v204 offset:39936
	global_load_lds_dwordx4 v218, s[14:15]
	s_mov_b32 m0, s56
	s_nop 0
	global_load_lds_dwordx4 v216, s[14:15]
	s_waitcnt vmcnt(8)
	s_waitcnt lgkmcnt(0)
	s_barrier
	s_waitcnt lgkmcnt(0)
	v_mfma_f32_16x16x32_bf16 v[160:163], v[108:111], v[164:167], v[160:163]
	v_mfma_f32_16x16x32_bf16 v[152:155], v[128:131], v[164:167], v[152:155]
	v_mfma_f32_16x16x32_bf16 v[120:123], v[108:111], v[172:175], v[120:123]
	v_mfma_f32_16x16x32_bf16 v[112:115], v[128:131], v[172:175], v[112:115]
	v_mfma_f32_16x16x32_bf16 v[96:99], v[108:111], v[180:183], v[96:99]
	v_mfma_f32_16x16x32_bf16 v[92:95], v[128:131], v[180:183], v[92:95]
	v_mfma_f32_16x16x32_bf16 v[80:83], v[108:111], v[188:191], v[80:83]
	v_mfma_f32_16x16x32_bf16 v[76:79], v[128:131], v[188:191], v[76:79]
	v_mfma_f32_16x16x32_bf16 v[160:163], v[116:119], v[168:171], v[160:163]
	v_mfma_f32_16x16x32_bf16 v[152:155], v[136:139], v[168:171], v[152:155]
	v_mfma_f32_16x16x32_bf16 v[120:123], v[116:119], v[176:179], v[120:123]
	v_mfma_f32_16x16x32_bf16 v[112:115], v[136:139], v[176:179], v[112:115]
	v_mfma_f32_16x16x32_bf16 v[96:99], v[116:119], v[184:187], v[96:99]
	v_mfma_f32_16x16x32_bf16 v[92:95], v[136:139], v[184:187], v[92:95]
	v_mfma_f32_16x16x32_bf16 v[80:83], v[116:119], v[192:195], v[80:83]
	v_mfma_f32_16x16x32_bf16 v[76:79], v[136:139], v[192:195], v[76:79]
	v_mfma_f32_16x16x32_bf16 v[132:135], v[140:143], v[164:167], v[132:135]
	v_mfma_f32_16x16x32_bf16 v[124:127], v[148:151], v[164:167], v[124:127]
	v_mfma_f32_16x16x32_bf16 v[104:107], v[140:143], v[172:175], v[104:107]
	v_mfma_f32_16x16x32_bf16 v[100:103], v[148:151], v[172:175], v[100:103]
	v_mfma_f32_16x16x32_bf16 v[88:91], v[140:143], v[180:183], v[88:91]
	v_mfma_f32_16x16x32_bf16 v[84:87], v[148:151], v[180:183], v[84:87]
	v_mfma_f32_16x16x32_bf16 v[72:75], v[140:143], v[188:191], v[72:75]
	v_mfma_f32_16x16x32_bf16 v[68:71], v[148:151], v[188:191], v[68:71]
	v_mfma_f32_16x16x32_bf16 v[132:135], v[144:147], v[168:171], v[132:135]
	v_mfma_f32_16x16x32_bf16 v[124:127], v[156:159], v[168:171], v[124:127]
	v_mfma_f32_16x16x32_bf16 v[104:107], v[144:147], v[176:179], v[104:107]
	v_mfma_f32_16x16x32_bf16 v[100:103], v[156:159], v[176:179], v[100:103]
	v_mfma_f32_16x16x32_bf16 v[88:91], v[144:147], v[184:187], v[88:91]
	v_mfma_f32_16x16x32_bf16 v[84:87], v[156:159], v[184:187], v[84:87]
	v_mfma_f32_16x16x32_bf16 v[72:75], v[144:147], v[192:195], v[72:75]
	v_mfma_f32_16x16x32_bf16 v[68:71], v[156:159], v[192:195], v[68:71]
	s_barrier
	s_add_u32 s14, s34, 0x8000
	s_addc_u32 s15, s35, 0
	s_add_i32 s48, s67, s52
	s_mov_b32 m0, s48
	ds_read_b128 v[164:167], v204 offset:49152
	ds_read_b128 v[168:171], v204 offset:50176
	ds_read_b128 v[172:175], v204 offset:51200
	ds_read_b128 v[176:179], v204 offset:52224
	ds_read_b128 v[180:183], v204 offset:53248
	ds_read_b128 v[184:187], v204 offset:54272
	ds_read_b128 v[188:191], v204 offset:55296
	ds_read_b128 v[192:195], v204 offset:56320
	global_load_lds_dwordx4 v2, s[14:15]
	s_add_i32 m0, s48, 0x2000
	s_nop 0
	global_load_lds_dwordx4 v214, s[14:15]
	s_add_u32 s14, s34, 0xc000
	s_addc_u32 s15, s35, 0
	s_add_i32 s34, s68, s52
	s_mov_b32 m0, s34
	s_nop 0
	global_load_lds_dwordx4 v2, s[14:15]
	s_add_i32 m0, s34, 0x2000
	s_nop 0
	global_load_lds_dwordx4 v214, s[14:15]
	s_mov_b32 m0, s57
	s_nop 0
	global_load_lds_dwordx4 v218, s[98:99]
	s_mov_b32 m0, s58
	s_nop 0
	global_load_lds_dwordx4 v216, s[98:99]
	s_waitcnt vmcnt(8)
	s_waitcnt lgkmcnt(0)
	s_barrier
	s_waitcnt lgkmcnt(0)
	v_mfma_f32_16x16x32_bf16 v[64:67], v[108:111], v[164:167], v[64:67]
	v_mfma_f32_16x16x32_bf16 v[60:63], v[128:131], v[164:167], v[60:63]
	v_mfma_f32_16x16x32_bf16 v[48:51], v[108:111], v[172:175], v[48:51]
	v_mfma_f32_16x16x32_bf16 v[44:47], v[128:131], v[172:175], v[44:47]
	v_mfma_f32_16x16x32_bf16 v[32:35], v[108:111], v[180:183], v[32:35]
	v_mfma_f32_16x16x32_bf16 v[28:31], v[128:131], v[180:183], v[28:31]
	v_mfma_f32_16x16x32_bf16 v[16:19], v[108:111], v[188:191], v[16:19]
	v_mfma_f32_16x16x32_bf16 v[12:15], v[128:131], v[188:191], v[12:15]
	v_mfma_f32_16x16x32_bf16 v[64:67], v[116:119], v[168:171], v[64:67]
	v_mfma_f32_16x16x32_bf16 v[60:63], v[136:139], v[168:171], v[60:63]
	v_mfma_f32_16x16x32_bf16 v[48:51], v[116:119], v[176:179], v[48:51]
	v_mfma_f32_16x16x32_bf16 v[44:47], v[136:139], v[176:179], v[44:47]
	v_mfma_f32_16x16x32_bf16 v[32:35], v[116:119], v[184:187], v[32:35]
	v_mfma_f32_16x16x32_bf16 v[28:31], v[136:139], v[184:187], v[28:31]
	v_mfma_f32_16x16x32_bf16 v[16:19], v[116:119], v[192:195], v[16:19]
	v_mfma_f32_16x16x32_bf16 v[12:15], v[136:139], v[192:195], v[12:15]
	v_mfma_f32_16x16x32_bf16 v[56:59], v[140:143], v[164:167], v[56:59]
	v_mfma_f32_16x16x32_bf16 v[52:55], v[148:151], v[164:167], v[52:55]
	v_mfma_f32_16x16x32_bf16 v[40:43], v[140:143], v[172:175], v[40:43]
	v_mfma_f32_16x16x32_bf16 v[36:39], v[148:151], v[172:175], v[36:39]
	v_mfma_f32_16x16x32_bf16 v[24:27], v[140:143], v[180:183], v[24:27]
	v_mfma_f32_16x16x32_bf16 v[20:23], v[148:151], v[180:183], v[20:23]
	v_mfma_f32_16x16x32_bf16 v[8:11], v[140:143], v[188:191], v[8:11]
	v_mfma_f32_16x16x32_bf16 v[4:7], v[148:151], v[188:191], v[4:7]
	v_mfma_f32_16x16x32_bf16 v[56:59], v[144:147], v[168:171], v[56:59]
	v_mfma_f32_16x16x32_bf16 v[52:55], v[156:159], v[168:171], v[52:55]
	v_mfma_f32_16x16x32_bf16 v[40:43], v[144:147], v[176:179], v[40:43]
	v_mfma_f32_16x16x32_bf16 v[36:39], v[156:159], v[176:179], v[36:39]
	v_mfma_f32_16x16x32_bf16 v[24:27], v[144:147], v[184:187], v[24:27]
	v_mfma_f32_16x16x32_bf16 v[20:23], v[156:159], v[184:187], v[20:23]
	v_mfma_f32_16x16x32_bf16 v[8:11], v[144:147], v[192:195], v[8:11]
	v_mfma_f32_16x16x32_bf16 v[4:7], v[156:159], v[192:195], v[4:7]
	s_barrier
	s_add_i32 s66, s66, 2
	s_add_u32 s64, s64, 0x10000
	s_addc_u32 s65, s65, 0
	s_cmpk_gt_u32 s66, 0x55
	s_mov_b64 s[14:15], s[22:23]
	s_cbranch_scc0 .LBB0_223
	s_and_b64 vcc, exec, s[6:7]
	s_cbranch_vccz .LBB0_226
	s_barrier

.LBB0_325:
	s_ashr_i32 s13, s12, 31
	s_lshl_b64 s[14:15], s[12:13], 20
	s_add_u32 s14, s10, s14
	s_addc_u32 s15, s11, s15
	s_and_b64 s[22:23], s[38:39], exec
	s_cselect_b32 s13, s15, s41
	s_cselect_b32 s54, s14, s40
	s_ashr_i32 s9, s8, 31
	s_lshl_b64 s[22:23], s[8:9], 20
	v_readlane_b32 s9, v254, 41
	s_add_u32 s22, s9, s22
	v_readlane_b32 s9, v254, 42
	s_addc_u32 s23, s9, s23
	s_and_b64 s[42:43], s[38:39], exec
	s_cselect_b32 s9, s23, s35
	s_cselect_b32 s55, s22, s34
	s_add_u32 s56, s34, 0x10000
	s_addc_u32 s57, s35, 0
	s_add_u32 s34, s40, 0x80080
	v_mov_b32_e32 v4, 0
	s_addc_u32 s35, s41, 0
	s_mov_b32 s58, -2
	v_mov_b32_e32 v5, v4
	v_mov_b32_e32 v6, v4
	v_mov_b32_e32 v7, v4
	v_mov_b32_e32 v8, v4
	v_mov_b32_e32 v9, v4
	v_mov_b32_e32 v10, v4
	v_mov_b32_e32 v11, v4
	v_mov_b32_e32 v20, v4
	v_mov_b32_e32 v21, v4
	v_mov_b32_e32 v22, v4
	v_mov_b32_e32 v23, v4
	v_mov_b32_e32 v24, v4
	v_mov_b32_e32 v25, v4
	v_mov_b32_e32 v26, v4
	v_mov_b32_e32 v27, v4
	v_mov_b32_e32 v36, v4
	v_mov_b32_e32 v37, v4
	v_mov_b32_e32 v38, v4
	v_mov_b32_e32 v39, v4
	v_mov_b32_e32 v40, v4
	v_mov_b32_e32 v41, v4
	v_mov_b32_e32 v42, v4
	v_mov_b32_e32 v43, v4
	v_mov_b32_e32 v52, v4
	v_mov_b32_e32 v53, v4
	v_mov_b32_e32 v54, v4
	v_mov_b32_e32 v55, v4
	v_mov_b32_e32 v56, v4
	v_mov_b32_e32 v57, v4
	v_mov_b32_e32 v58, v4
	v_mov_b32_e32 v59, v4
	v_mov_b32_e32 v12, v4
	v_mov_b32_e32 v13, v4
	v_mov_b32_e32 v14, v4
	v_mov_b32_e32 v15, v4
	v_mov_b32_e32 v16, v4
	v_mov_b32_e32 v17, v4
	v_mov_b32_e32 v18, v4
	v_mov_b32_e32 v19, v4
	v_mov_b32_e32 v28, v4
	v_mov_b32_e32 v29, v4
	v_mov_b32_e32 v30, v4
	v_mov_b32_e32 v31, v4
	v_mov_b32_e32 v32, v4
	v_mov_b32_e32 v33, v4
	v_mov_b32_e32 v34, v4
	v_mov_b32_e32 v35, v4
	v_mov_b32_e32 v44, v4
	v_mov_b32_e32 v45, v4
	v_mov_b32_e32 v46, v4
	v_mov_b32_e32 v47, v4
	v_mov_b32_e32 v48, v4
	v_mov_b32_e32 v49, v4
	v_mov_b32_e32 v50, v4
	v_mov_b32_e32 v51, v4
	v_mov_b32_e32 v60, v4
	v_mov_b32_e32 v61, v4
	v_mov_b32_e32 v62, v4
	v_mov_b32_e32 v63, v4
	v_mov_b32_e32 v64, v4
	v_mov_b32_e32 v65, v4
	v_mov_b32_e32 v66, v4
	v_mov_b32_e32 v67, v4
	v_mov_b32_e32 v68, v4
	v_mov_b32_e32 v69, v4
	v_mov_b32_e32 v70, v4
	v_mov_b32_e32 v71, v4
	v_mov_b32_e32 v72, v4
	v_mov_b32_e32 v73, v4
	v_mov_b32_e32 v74, v4
	v_mov_b32_e32 v75, v4
	v_mov_b32_e32 v84, v4
	v_mov_b32_e32 v85, v4
	v_mov_b32_e32 v86, v4
	v_mov_b32_e32 v87, v4
	v_mov_b32_e32 v88, v4
	v_mov_b32_e32 v89, v4
	v_mov_b32_e32 v90, v4
	v_mov_b32_e32 v91, v4
	v_mov_b32_e32 v100, v4
	v_mov_b32_e32 v101, v4
	v_mov_b32_e32 v102, v4
	v_mov_b32_e32 v103, v4
	v_mov_b32_e32 v104, v4
	v_mov_b32_e32 v105, v4
	v_mov_b32_e32 v106, v4
	v_mov_b32_e32 v107, v4
	v_mov_b32_e32 v116, v4
	v_mov_b32_e32 v117, v4
	v_mov_b32_e32 v118, v4
	v_mov_b32_e32 v119, v4
	v_mov_b32_e32 v120, v4
	v_mov_b32_e32 v121, v4
	v_mov_b32_e32 v122, v4
	v_mov_b32_e32 v123, v4
	v_mov_b32_e32 v76, v4
	v_mov_b32_e32 v77, v4
	v_mov_b32_e32 v78, v4
	v_mov_b32_e32 v79, v4
	v_mov_b32_e32 v80, v4
	v_mov_b32_e32 v81, v4
	v_mov_b32_e32 v82, v4
	v_mov_b32_e32 v83, v4
	v_mov_b32_e32 v92, v4
	v_mov_b32_e32 v93, v4
	v_mov_b32_e32 v94, v4
	v_mov_b32_e32 v95, v4
	v_mov_b32_e32 v96, v4
	v_mov_b32_e32 v97, v4
	v_mov_b32_e32 v98, v4
	v_mov_b32_e32 v99, v4
	v_mov_b32_e32 v108, v4
	v_mov_b32_e32 v109, v4
	v_mov_b32_e32 v110, v4
	v_mov_b32_e32 v111, v4
	v_mov_b32_e32 v112, v4
	v_mov_b32_e32 v113, v4
	v_mov_b32_e32 v114, v4
	v_mov_b32_e32 v115, v4
	v_mov_b32_e32 v124, v4
	v_mov_b32_e32 v125, v4
	v_mov_b32_e32 v126, v4
	v_mov_b32_e32 v127, v4
	v_mov_b32_e32 v128, v4
	v_mov_b32_e32 v129, v4
	v_mov_b32_e32 v130, v4
	v_mov_b32_e32 v131, v4
	v_add_u32_e32 v228, 0x10000, v147
.LBB0_326:
	s_add_u32 s40, s34, 0xfff80080
	s_addc_u32 s41, s35, -1
	s_add_i32 s59, 0, 0x10000
	s_cmp_eq_u32 s58, 28
	s_cselect_b32 s43, s13, s41
	s_cselect_b32 s42, s54, s40
	s_cselect_b32 s41, s9, s57
	s_cselect_b32 s40, s55, s56
	s_add_i32 s62, 0, 0x14000
	ds_read_b128 v[142:145], v228
	ds_read_b128 v[152:155], v228 offset:1024
	ds_read_b128 v[156:159], v228 offset:2048
	ds_read_b128 v[160:163], v228 offset:3072
	ds_read_b128 v[164:167], v228 offset:16384
	ds_read_b128 v[168:171], v228 offset:17408
	ds_read_b128 v[172:175], v228 offset:18432
	ds_read_b128 v[176:179], v228 offset:19456
	s_add_i32 m0, s45, 0xc000
	ds_read_b128 v[180:183], v151
	ds_read_b128 v[184:187], v151 offset:1024
	ds_read_b128 v[188:191], v151 offset:2048
	ds_read_b128 v[192:195], v151 offset:3072
	ds_read_b128 v[202:205], v151 offset:4096
	ds_read_b128 v[214:217], v151 offset:5120
	ds_read_b128 v[218:221], v151 offset:6144
	ds_read_b128 v[222:225], v151 offset:7168
	global_load_lds_dwordx4 v138, s[34:35]
	s_add_i32 m0, s45, 0xe000
	s_nop 0
	global_load_lds_dwordx4 v140, s[34:35]
	s_waitcnt vmcnt(8)
	s_waitcnt lgkmcnt(0)
	s_barrier
	s_waitcnt lgkmcnt(0)
	v_mfma_f32_16x16x32_bf16 v[128:131], v[142:145], v[180:183], v[128:131]
	v_mfma_f32_16x16x32_bf16 v[124:127], v[156:159], v[180:183], v[124:127]
	v_mfma_f32_16x16x32_bf16 v[112:115], v[142:145], v[188:191], v[112:115]
	v_mfma_f32_16x16x32_bf16 v[108:111], v[156:159], v[188:191], v[108:111]
	v_mfma_f32_16x16x32_bf16 v[96:99], v[142:145], v[202:205], v[96:99]
	v_mfma_f32_16x16x32_bf16 v[92:95], v[156:159], v[202:205], v[92:95]
	v_mfma_f32_16x16x32_bf16 v[80:83], v[142:145], v[218:221], v[80:83]
	v_mfma_f32_16x16x32_bf16 v[76:79], v[156:159], v[218:221], v[76:79]
	v_mfma_f32_16x16x32_bf16 v[128:131], v[152:155], v[184:187], v[128:131]
	v_mfma_f32_16x16x32_bf16 v[124:127], v[160:163], v[184:187], v[124:127]
	v_mfma_f32_16x16x32_bf16 v[112:115], v[152:155], v[192:195], v[112:115]
	v_mfma_f32_16x16x32_bf16 v[108:111], v[160:163], v[192:195], v[108:111]
	v_mfma_f32_16x16x32_bf16 v[96:99], v[152:155], v[214:217], v[96:99]
	v_mfma_f32_16x16x32_bf16 v[92:95], v[160:163], v[214:217], v[92:95]
	v_mfma_f32_16x16x32_bf16 v[80:83], v[152:155], v[222:225], v[80:83]
	v_mfma_f32_16x16x32_bf16 v[76:79], v[160:163], v[222:225], v[76:79]
	v_mfma_f32_16x16x32_bf16 v[120:123], v[164:167], v[180:183], v[120:123]
	v_mfma_f32_16x16x32_bf16 v[116:119], v[172:175], v[180:183], v[116:119]
	v_mfma_f32_16x16x32_bf16 v[104:107], v[164:167], v[188:191], v[104:107]
	v_mfma_f32_16x16x32_bf16 v[100:103], v[172:175], v[188:191], v[100:103]
	v_mfma_f32_16x16x32_bf16 v[88:91], v[164:167], v[202:205], v[88:91]
	v_mfma_f32_16x16x32_bf16 v[84:87], v[172:175], v[202:205], v[84:87]
	v_mfma_f32_16x16x32_bf16 v[72:75], v[164:167], v[218:221], v[72:75]
	v_mfma_f32_16x16x32_bf16 v[68:71], v[172:175], v[218:221], v[68:71]
	v_mfma_f32_16x16x32_bf16 v[120:123], v[168:171], v[184:187], v[120:123]
	v_mfma_f32_16x16x32_bf16 v[116:119], v[176:179], v[184:187], v[116:119]
	v_mfma_f32_16x16x32_bf16 v[104:107], v[168:171], v[192:195], v[104:107]
	v_mfma_f32_16x16x32_bf16 v[100:103], v[176:179], v[192:195], v[100:103]
	v_mfma_f32_16x16x32_bf16 v[88:91], v[168:171], v[214:217], v[88:91]
	v_mfma_f32_16x16x32_bf16 v[84:87], v[176:179], v[214:217], v[84:87]
	v_mfma_f32_16x16x32_bf16 v[72:75], v[168:171], v[222:225], v[72:75]
	v_mfma_f32_16x16x32_bf16 v[68:71], v[176:179], v[222:225], v[68:71]
	s_barrier
	s_add_u32 s98, s42, s4
	s_addc_u32 s99, s43, s5
	s_add_i32 s59, s59, s44
	s_mov_b32 m0, s59
	ds_read_b128 v[180:183], v151 offset:16384
	ds_read_b128 v[184:187], v151 offset:17408
	ds_read_b128 v[188:191], v151 offset:18432
	ds_read_b128 v[192:195], v151 offset:19456
	ds_read_b128 v[202:205], v151 offset:20480
	ds_read_b128 v[214:217], v151 offset:21504
	ds_read_b128 v[218:221], v151 offset:22528
	ds_read_b128 v[222:225], v151 offset:23552
	global_load_lds_dwordx4 v2, s[40:41]
	s_add_i32 m0, s59, 0x2000
	s_add_u32 s60, s40, 0x4000
	s_addc_u32 s61, s41, 0
	s_add_i32 s59, s62, s44
	global_load_lds_dwordx4 v132, s[40:41]
	s_mov_b32 m0, s59
	s_nop 0
	global_load_lds_dwordx4 v2, s[60:61]
	s_add_i32 m0, s59, 0x2000
	s_nop 0
	global_load_lds_dwordx4 v132, s[60:61]
	s_mov_b32 m0, s45
	s_nop 0
	global_load_lds_dwordx4 v136, s[42:43]
	s_mov_b32 m0, s46
	s_nop 0
	global_load_lds_dwordx4 v134, s[42:43]
	s_waitcnt vmcnt(8)
	s_waitcnt lgkmcnt(0)
	s_barrier
	s_waitcnt lgkmcnt(0)
	v_mfma_f32_16x16x32_bf16 v[64:67], v[142:145], v[180:183], v[64:67]
	v_mfma_f32_16x16x32_bf16 v[60:63], v[156:159], v[180:183], v[60:63]
	v_mfma_f32_16x16x32_bf16 v[48:51], v[142:145], v[188:191], v[48:51]
	v_mfma_f32_16x16x32_bf16 v[44:47], v[156:159], v[188:191], v[44:47]
	v_mfma_f32_16x16x32_bf16 v[32:35], v[142:145], v[202:205], v[32:35]
	v_mfma_f32_16x16x32_bf16 v[28:31], v[156:159], v[202:205], v[28:31]
	v_mfma_f32_16x16x32_bf16 v[16:19], v[142:145], v[218:221], v[16:19]
	v_mfma_f32_16x16x32_bf16 v[12:15], v[156:159], v[218:221], v[12:15]
	v_mfma_f32_16x16x32_bf16 v[64:67], v[152:155], v[184:187], v[64:67]
	v_mfma_f32_16x16x32_bf16 v[60:63], v[160:163], v[184:187], v[60:63]
	v_mfma_f32_16x16x32_bf16 v[48:51], v[152:155], v[192:195], v[48:51]
	v_mfma_f32_16x16x32_bf16 v[44:47], v[160:163], v[192:195], v[44:47]
	v_mfma_f32_16x16x32_bf16 v[32:35], v[152:155], v[214:217], v[32:35]
	v_mfma_f32_16x16x32_bf16 v[28:31], v[160:163], v[214:217], v[28:31]
	v_mfma_f32_16x16x32_bf16 v[16:19], v[152:155], v[222:225], v[16:19]
	v_mfma_f32_16x16x32_bf16 v[12:15], v[160:163], v[222:225], v[12:15]
	v_mfma_f32_16x16x32_bf16 v[56:59], v[164:167], v[180:183], v[56:59]
	v_mfma_f32_16x16x32_bf16 v[52:55], v[172:175], v[180:183], v[52:55]
	v_mfma_f32_16x16x32_bf16 v[40:43], v[164:167], v[188:191], v[40:43]
	v_mfma_f32_16x16x32_bf16 v[36:39], v[172:175], v[188:191], v[36:39]
	v_mfma_f32_16x16x32_bf16 v[24:27], v[164:167], v[202:205], v[24:27]
	v_mfma_f32_16x16x32_bf16 v[20:23], v[172:175], v[202:205], v[20:23]
	v_mfma_f32_16x16x32_bf16 v[8:11], v[164:167], v[218:221], v[8:11]
	v_mfma_f32_16x16x32_bf16 v[4:7], v[172:175], v[218:221], v[4:7]
	v_mfma_f32_16x16x32_bf16 v[56:59], v[168:171], v[184:187], v[56:59]
	v_mfma_f32_16x16x32_bf16 v[52:55], v[176:179], v[184:187], v[52:55]
	v_mfma_f32_16x16x32_bf16 v[40:43], v[168:171], v[192:195], v[40:43]
	v_mfma_f32_16x16x32_bf16 v[36:39], v[176:179], v[192:195], v[36:39]
	v_mfma_f32_16x16x32_bf16 v[24:27], v[168:171], v[214:217], v[24:27]
	v_mfma_f32_16x16x32_bf16 v[20:23], v[176:179], v[214:217], v[20:23]
	v_mfma_f32_16x16x32_bf16 v[8:11], v[168:171], v[222:225], v[8:11]
	v_mfma_f32_16x16x32_bf16 v[4:7], v[176:179], v[222:225], v[4:7]
	s_barrier
	s_add_i32 s59, 0, 0x18000
	s_add_i32 s60, 0, 0x1c000
	ds_read_b128 v[142:145], v228 offset:32768
	ds_read_b128 v[152:155], v228 offset:33792
	ds_read_b128 v[156:159], v228 offset:34816
	ds_read_b128 v[160:163], v228 offset:35840
	ds_read_b128 v[164:167], v228 offset:49152
	ds_read_b128 v[168:171], v228 offset:50176
	ds_read_b128 v[172:175], v228 offset:51200
	ds_read_b128 v[176:179], v228 offset:52224
	s_add_u32 s42, s42, 0x80000
	s_addc_u32 s43, s43, 0
	s_mov_b32 m0, s47
	ds_read_b128 v[180:183], v151 offset:32768
	ds_read_b128 v[184:187], v151 offset:33792
	ds_read_b128 v[188:191], v151 offset:34816
	ds_read_b128 v[192:195], v151 offset:35840
	ds_read_b128 v[202:205], v151 offset:36864
	ds_read_b128 v[214:217], v151 offset:37888
	ds_read_b128 v[218:221], v151 offset:38912
	ds_read_b128 v[222:225], v151 offset:39936
	global_load_lds_dwordx4 v136, s[42:43]
	s_mov_b32 m0, s48
	s_nop 0
	global_load_lds_dwordx4 v134, s[42:43]
	s_waitcnt vmcnt(8)
	s_waitcnt lgkmcnt(0)
	s_barrier
	s_waitcnt lgkmcnt(0)
	v_mfma_f32_16x16x32_bf16 v[128:131], v[142:145], v[180:183], v[128:131]
	v_mfma_f32_16x16x32_bf16 v[124:127], v[156:159], v[180:183], v[124:127]
	v_mfma_f32_16x16x32_bf16 v[112:115], v[142:145], v[188:191], v[112:115]
	v_mfma_f32_16x16x32_bf16 v[108:111], v[156:159], v[188:191], v[108:111]
	v_mfma_f32_16x16x32_bf16 v[96:99], v[142:145], v[202:205], v[96:99]
	v_mfma_f32_16x16x32_bf16 v[92:95], v[156:159], v[202:205], v[92:95]
	v_mfma_f32_16x16x32_bf16 v[80:83], v[142:145], v[218:221], v[80:83]
	v_mfma_f32_16x16x32_bf16 v[76:79], v[156:159], v[218:221], v[76:79]
	v_mfma_f32_16x16x32_bf16 v[128:131], v[152:155], v[184:187], v[128:131]
	v_mfma_f32_16x16x32_bf16 v[124:127], v[160:163], v[184:187], v[124:127]
	v_mfma_f32_16x16x32_bf16 v[112:115], v[152:155], v[192:195], v[112:115]
	v_mfma_f32_16x16x32_bf16 v[108:111], v[160:163], v[192:195], v[108:111]
	v_mfma_f32_16x16x32_bf16 v[96:99], v[152:155], v[214:217], v[96:99]
	v_mfma_f32_16x16x32_bf16 v[92:95], v[160:163], v[214:217], v[92:95]
	v_mfma_f32_16x16x32_bf16 v[80:83], v[152:155], v[222:225], v[80:83]
	v_mfma_f32_16x16x32_bf16 v[76:79], v[160:163], v[222:225], v[76:79]
	v_mfma_f32_16x16x32_bf16 v[120:123], v[164:167], v[180:183], v[120:123]
	v_mfma_f32_16x16x32_bf16 v[116:119], v[172:175], v[180:183], v[116:119]
	v_mfma_f32_16x16x32_bf16 v[104:107], v[164:167], v[188:191], v[104:107]
	v_mfma_f32_16x16x32_bf16 v[100:103], v[172:175], v[188:191], v[100:103]
	v_mfma_f32_16x16x32_bf16 v[88:91], v[164:167], v[202:205], v[88:91]
	v_mfma_f32_16x16x32_bf16 v[84:87], v[172:175], v[202:205], v[84:87]
	v_mfma_f32_16x16x32_bf16 v[72:75], v[164:167], v[218:221], v[72:75]
	v_mfma_f32_16x16x32_bf16 v[68:71], v[172:175], v[218:221], v[68:71]
	v_mfma_f32_16x16x32_bf16 v[120:123], v[168:171], v[184:187], v[120:123]
	v_mfma_f32_16x16x32_bf16 v[116:119], v[176:179], v[184:187], v[116:119]
	v_mfma_f32_16x16x32_bf16 v[104:107], v[168:171], v[192:195], v[104:107]
	v_mfma_f32_16x16x32_bf16 v[100:103], v[176:179], v[192:195], v[100:103]
	v_mfma_f32_16x16x32_bf16 v[88:91], v[168:171], v[214:217], v[88:91]
	v_mfma_f32_16x16x32_bf16 v[84:87], v[176:179], v[214:217], v[84:87]
	v_mfma_f32_16x16x32_bf16 v[72:75], v[168:171], v[222:225], v[72:75]
	v_mfma_f32_16x16x32_bf16 v[68:71], v[176:179], v[222:225], v[68:71]
	s_barrier
	s_add_u32 s42, s40, 0x8000
	s_addc_u32 s43, s41, 0
	s_add_i32 s59, s59, s44
	s_mov_b32 m0, s59
	ds_read_b128 v[180:183], v151 offset:49152
	ds_read_b128 v[184:187], v151 offset:50176
	ds_read_b128 v[188:191], v151 offset:51200
	ds_read_b128 v[192:195], v151 offset:52224
	ds_read_b128 v[202:205], v151 offset:53248
	ds_read_b128 v[214:217], v151 offset:54272
	ds_read_b128 v[218:221], v151 offset:55296
	ds_read_b128 v[222:225], v151 offset:56320
	global_load_lds_dwordx4 v2, s[42:43]
	s_add_i32 m0, s59, 0x2000
	s_add_u32 s40, s40, 0xc000
	s_addc_u32 s41, s41, 0
	global_load_lds_dwordx4 v132, s[42:43]
	s_add_i32 s42, s60, s44
	s_mov_b32 m0, s42
	s_nop 0
	global_load_lds_dwordx4 v2, s[40:41]
	s_add_i32 m0, s42, 0x2000
	s_nop 0
	global_load_lds_dwordx4 v132, s[40:41]
	s_mov_b32 m0, s49
	s_nop 0
	global_load_lds_dwordx4 v136, s[98:99]
	s_mov_b32 m0, s50
	s_nop 0
	global_load_lds_dwordx4 v134, s[98:99]
	s_waitcnt vmcnt(8)
	s_waitcnt lgkmcnt(0)
	s_barrier
	s_waitcnt lgkmcnt(0)
	v_mfma_f32_16x16x32_bf16 v[64:67], v[142:145], v[180:183], v[64:67]
	v_mfma_f32_16x16x32_bf16 v[60:63], v[156:159], v[180:183], v[60:63]
	v_mfma_f32_16x16x32_bf16 v[48:51], v[142:145], v[188:191], v[48:51]
	v_mfma_f32_16x16x32_bf16 v[44:47], v[156:159], v[188:191], v[44:47]
	v_mfma_f32_16x16x32_bf16 v[32:35], v[142:145], v[202:205], v[32:35]
	v_mfma_f32_16x16x32_bf16 v[28:31], v[156:159], v[202:205], v[28:31]
	v_mfma_f32_16x16x32_bf16 v[16:19], v[142:145], v[218:221], v[16:19]
	v_mfma_f32_16x16x32_bf16 v[12:15], v[156:159], v[218:221], v[12:15]
	v_mfma_f32_16x16x32_bf16 v[64:67], v[152:155], v[184:187], v[64:67]
	v_mfma_f32_16x16x32_bf16 v[60:63], v[160:163], v[184:187], v[60:63]
	v_mfma_f32_16x16x32_bf16 v[48:51], v[152:155], v[192:195], v[48:51]
	v_mfma_f32_16x16x32_bf16 v[44:47], v[160:163], v[192:195], v[44:47]
	v_mfma_f32_16x16x32_bf16 v[32:35], v[152:155], v[214:217], v[32:35]
	v_mfma_f32_16x16x32_bf16 v[28:31], v[160:163], v[214:217], v[28:31]
	v_mfma_f32_16x16x32_bf16 v[16:19], v[152:155], v[222:225], v[16:19]
	v_mfma_f32_16x16x32_bf16 v[12:15], v[160:163], v[222:225], v[12:15]
	v_mfma_f32_16x16x32_bf16 v[56:59], v[164:167], v[180:183], v[56:59]
	v_mfma_f32_16x16x32_bf16 v[52:55], v[172:175], v[180:183], v[52:55]
	v_mfma_f32_16x16x32_bf16 v[40:43], v[164:167], v[188:191], v[40:43]
	v_mfma_f32_16x16x32_bf16 v[36:39], v[172:175], v[188:191], v[36:39]
	v_mfma_f32_16x16x32_bf16 v[24:27], v[164:167], v[202:205], v[24:27]
	v_mfma_f32_16x16x32_bf16 v[20:23], v[172:175], v[202:205], v[20:23]
	v_mfma_f32_16x16x32_bf16 v[8:11], v[164:167], v[218:221], v[8:11]
	v_mfma_f32_16x16x32_bf16 v[4:7], v[172:175], v[218:221], v[4:7]
	v_mfma_f32_16x16x32_bf16 v[56:59], v[168:171], v[184:187], v[56:59]
	v_mfma_f32_16x16x32_bf16 v[52:55], v[176:179], v[184:187], v[52:55]
	v_mfma_f32_16x16x32_bf16 v[40:43], v[168:171], v[192:195], v[40:43]
	v_mfma_f32_16x16x32_bf16 v[36:39], v[176:179], v[192:195], v[36:39]
	v_mfma_f32_16x16x32_bf16 v[24:27], v[168:171], v[214:217], v[24:27]
	v_mfma_f32_16x16x32_bf16 v[20:23], v[176:179], v[214:217], v[20:23]
	v_mfma_f32_16x16x32_bf16 v[8:11], v[168:171], v[222:225], v[8:11]
	v_mfma_f32_16x16x32_bf16 v[4:7], v[176:179], v[222:225], v[4:7]
	s_barrier
	s_add_i32 s58, s58, 2
	s_add_u32 s56, s56, 0x10000
	s_addc_u32 s57, s57, 0
	s_add_u32 s34, s34, 0x100
	s_addc_u32 s35, s35, 0
	s_cmp_gt_u32 s58, 29
	s_cbranch_scc0 .LBB0_326
	s_and_b64 vcc, exec, s[6:7]
	s_cbranch_vccz .LBB0_329
	s_barrier

.LBB0_365:
	s_ashr_i32 s51, s50, 31
	s_lshl_b64 s[8:9], s[50:51], 20
	s_add_u32 s52, s10, s8
	s_addc_u32 s53, s11, s9
	s_and_b64 s[8:9], s[40:41], exec
	s_cselect_b32 s43, s53, s7
	s_cselect_b32 s51, s52, s6
	s_ashr_i32 s49, s48, 31
	s_lshl_b64 s[8:9], s[48:49], 20
	v_readlane_b32 s49, v254, 41
	s_add_u32 s54, s49, s8
	v_readlane_b32 s8, v254, 42
	s_addc_u32 s55, s8, s9
	s_and_b64 s[8:9], s[40:41], exec
	s_cselect_b32 s49, s55, s1
	s_cselect_b32 s58, s54, s0
	s_add_u32 s59, s0, 0x10000
	s_addc_u32 s60, s1, 0
	s_add_u32 s0, s6, 0x80080
	v_mov_b32_e32 v4, 0
	s_addc_u32 s1, s7, 0
	s_mov_b32 s61, -2
	s_waitcnt lgkmcnt(0)
	v_mov_b32_e32 v5, v4
	v_mov_b32_e32 v6, v4
	v_mov_b32_e32 v7, v4
	v_mov_b32_e32 v8, v4
	v_mov_b32_e32 v9, v4
	v_mov_b32_e32 v10, v4
	v_mov_b32_e32 v11, v4
	v_mov_b32_e32 v20, v4
	v_mov_b32_e32 v21, v4
	v_mov_b32_e32 v22, v4
	v_mov_b32_e32 v23, v4
	v_mov_b32_e32 v24, v4
	v_mov_b32_e32 v25, v4
	v_mov_b32_e32 v26, v4
	v_mov_b32_e32 v27, v4
	v_mov_b32_e32 v36, v4
	v_mov_b32_e32 v37, v4
	v_mov_b32_e32 v38, v4
	v_mov_b32_e32 v39, v4
	v_mov_b32_e32 v40, v4
	v_mov_b32_e32 v41, v4
	v_mov_b32_e32 v42, v4
	v_mov_b32_e32 v43, v4
	v_mov_b32_e32 v52, v4
	v_mov_b32_e32 v53, v4
	v_mov_b32_e32 v54, v4
	v_mov_b32_e32 v55, v4
	v_mov_b32_e32 v56, v4
	v_mov_b32_e32 v57, v4
	v_mov_b32_e32 v58, v4
	v_mov_b32_e32 v59, v4
	v_mov_b32_e32 v12, v4
	v_mov_b32_e32 v13, v4
	v_mov_b32_e32 v14, v4
	v_mov_b32_e32 v15, v4
	v_mov_b32_e32 v16, v4
	v_mov_b32_e32 v17, v4
	v_mov_b32_e32 v18, v4
	v_mov_b32_e32 v19, v4
	v_mov_b32_e32 v28, v4
	v_mov_b32_e32 v29, v4
	v_mov_b32_e32 v30, v4
	v_mov_b32_e32 v31, v4
	v_mov_b32_e32 v32, v4
	v_mov_b32_e32 v33, v4
	v_mov_b32_e32 v34, v4
	v_mov_b32_e32 v35, v4
	v_mov_b32_e32 v44, v4
	v_mov_b32_e32 v45, v4
	v_mov_b32_e32 v46, v4
	v_mov_b32_e32 v47, v4
	v_mov_b32_e32 v48, v4
	v_mov_b32_e32 v49, v4
	v_mov_b32_e32 v50, v4
	v_mov_b32_e32 v51, v4
	v_mov_b32_e32 v60, v4
	v_mov_b32_e32 v61, v4
	v_mov_b32_e32 v62, v4
	v_mov_b32_e32 v63, v4
	v_mov_b32_e32 v64, v4
	v_mov_b32_e32 v65, v4
	v_mov_b32_e32 v66, v4
	v_mov_b32_e32 v67, v4
	v_mov_b32_e32 v68, v4
	v_mov_b32_e32 v69, v4
	v_mov_b32_e32 v70, v4
	v_mov_b32_e32 v71, v4
	v_mov_b32_e32 v72, v4
	v_mov_b32_e32 v73, v4
	v_mov_b32_e32 v74, v4
	v_mov_b32_e32 v75, v4
	v_mov_b32_e32 v84, v4
	v_mov_b32_e32 v85, v4
	v_mov_b32_e32 v86, v4
	v_mov_b32_e32 v87, v4
	v_mov_b32_e32 v88, v4
	v_mov_b32_e32 v89, v4
	v_mov_b32_e32 v90, v4
	v_mov_b32_e32 v91, v4
	v_mov_b32_e32 v100, v4
	v_mov_b32_e32 v101, v4
	v_mov_b32_e32 v102, v4
	v_mov_b32_e32 v103, v4
	v_mov_b32_e32 v104, v4
	v_mov_b32_e32 v105, v4
	v_mov_b32_e32 v106, v4
	v_mov_b32_e32 v107, v4
	v_mov_b32_e32 v116, v4
	v_mov_b32_e32 v117, v4
	v_mov_b32_e32 v118, v4
	v_mov_b32_e32 v119, v4
	v_mov_b32_e32 v120, v4
	v_mov_b32_e32 v121, v4
	v_mov_b32_e32 v122, v4
	v_mov_b32_e32 v123, v4
	v_mov_b32_e32 v76, v4
	v_mov_b32_e32 v77, v4
	v_mov_b32_e32 v78, v4
	v_mov_b32_e32 v79, v4
	v_mov_b32_e32 v80, v4
	v_mov_b32_e32 v81, v4
	v_mov_b32_e32 v82, v4
	v_mov_b32_e32 v83, v4
	v_mov_b32_e32 v92, v4
	v_mov_b32_e32 v93, v4
	v_mov_b32_e32 v94, v4
	v_mov_b32_e32 v95, v4
	v_mov_b32_e32 v96, v4
	v_mov_b32_e32 v97, v4
	v_mov_b32_e32 v98, v4
	v_mov_b32_e32 v99, v4
	v_mov_b32_e32 v108, v4
	v_mov_b32_e32 v109, v4
	v_mov_b32_e32 v110, v4
	v_mov_b32_e32 v111, v4
	v_mov_b32_e32 v112, v4
	v_mov_b32_e32 v113, v4
	v_mov_b32_e32 v114, v4
	v_mov_b32_e32 v115, v4
	v_mov_b32_e32 v124, v4
	v_mov_b32_e32 v125, v4
	v_mov_b32_e32 v126, v4
	v_mov_b32_e32 v127, v4
	v_mov_b32_e32 v128, v4
	v_mov_b32_e32 v129, v4
	v_mov_b32_e32 v130, v4
	v_mov_b32_e32 v131, v4
	v_add_u32_e32 v230, 0x10000, v150
.LBB0_366:
	s_add_u32 s6, s0, 0xfff80080
	s_addc_u32 s7, s1, -1
	s_add_i32 s62, 0, 0x10000
	s_cmp_eq_u32 s61, 28
	s_cselect_b32 s9, s43, s7
	s_cselect_b32 s8, s51, s6
	s_cselect_b32 s7, s49, s60
	s_cselect_b32 s6, s58, s59
	s_add_i32 s64, 0, 0x14000
	ds_read_b128 v[142:145], v230
	ds_read_b128 v[156:159], v230 offset:1024
	ds_read_b128 v[160:163], v230 offset:2048
	ds_read_b128 v[164:167], v230 offset:3072
	ds_read_b128 v[168:171], v230 offset:16384
	ds_read_b128 v[172:175], v230 offset:17408
	ds_read_b128 v[176:179], v230 offset:18432
	ds_read_b128 v[180:183], v230 offset:19456
	s_add_i32 m0, s13, 0xc000
	ds_read_b128 v[184:187], v154
	ds_read_b128 v[188:191], v154 offset:1024
	ds_read_b128 v[192:195], v154 offset:2048
	ds_read_b128 v[202:205], v154 offset:3072
	ds_read_b128 v[214:217], v154 offset:4096
	ds_read_b128 v[218:221], v154 offset:5120
	ds_read_b128 v[222:225], v154 offset:6144
	ds_read_b128 v[226:229], v154 offset:7168
	global_load_lds_dwordx4 v138, s[0:1]
	s_add_i32 m0, s13, 0xe000
	s_nop 0
	global_load_lds_dwordx4 v140, s[0:1]
	s_waitcnt vmcnt(8)
	s_waitcnt lgkmcnt(0)
	s_barrier
	s_waitcnt lgkmcnt(0)
	v_mfma_f32_16x16x32_bf16 v[128:131], v[142:145], v[184:187], v[128:131]
	v_mfma_f32_16x16x32_bf16 v[124:127], v[160:163], v[184:187], v[124:127]
	v_mfma_f32_16x16x32_bf16 v[112:115], v[142:145], v[192:195], v[112:115]
	v_mfma_f32_16x16x32_bf16 v[108:111], v[160:163], v[192:195], v[108:111]
	v_mfma_f32_16x16x32_bf16 v[96:99], v[142:145], v[214:217], v[96:99]
	v_mfma_f32_16x16x32_bf16 v[92:95], v[160:163], v[214:217], v[92:95]
	v_mfma_f32_16x16x32_bf16 v[80:83], v[142:145], v[222:225], v[80:83]
	v_mfma_f32_16x16x32_bf16 v[76:79], v[160:163], v[222:225], v[76:79]
	v_mfma_f32_16x16x32_bf16 v[128:131], v[156:159], v[188:191], v[128:131]
	v_mfma_f32_16x16x32_bf16 v[124:127], v[164:167], v[188:191], v[124:127]
	v_mfma_f32_16x16x32_bf16 v[112:115], v[156:159], v[202:205], v[112:115]
	v_mfma_f32_16x16x32_bf16 v[108:111], v[164:167], v[202:205], v[108:111]
	v_mfma_f32_16x16x32_bf16 v[96:99], v[156:159], v[218:221], v[96:99]
	v_mfma_f32_16x16x32_bf16 v[92:95], v[164:167], v[218:221], v[92:95]
	v_mfma_f32_16x16x32_bf16 v[80:83], v[156:159], v[226:229], v[80:83]
	v_mfma_f32_16x16x32_bf16 v[76:79], v[164:167], v[226:229], v[76:79]
	v_mfma_f32_16x16x32_bf16 v[120:123], v[168:171], v[184:187], v[120:123]
	v_mfma_f32_16x16x32_bf16 v[116:119], v[176:179], v[184:187], v[116:119]
	v_mfma_f32_16x16x32_bf16 v[104:107], v[168:171], v[192:195], v[104:107]
	v_mfma_f32_16x16x32_bf16 v[100:103], v[176:179], v[192:195], v[100:103]
	v_mfma_f32_16x16x32_bf16 v[88:91], v[168:171], v[214:217], v[88:91]
	v_mfma_f32_16x16x32_bf16 v[84:87], v[176:179], v[214:217], v[84:87]
	v_mfma_f32_16x16x32_bf16 v[72:75], v[168:171], v[222:225], v[72:75]
	v_mfma_f32_16x16x32_bf16 v[68:71], v[176:179], v[222:225], v[68:71]
	v_mfma_f32_16x16x32_bf16 v[120:123], v[172:175], v[188:191], v[120:123]
	v_mfma_f32_16x16x32_bf16 v[116:119], v[180:183], v[188:191], v[116:119]
	v_mfma_f32_16x16x32_bf16 v[104:107], v[172:175], v[202:205], v[104:107]
	v_mfma_f32_16x16x32_bf16 v[100:103], v[180:183], v[202:205], v[100:103]
	v_mfma_f32_16x16x32_bf16 v[88:91], v[172:175], v[218:221], v[88:91]
	v_mfma_f32_16x16x32_bf16 v[84:87], v[180:183], v[218:221], v[84:87]
	v_mfma_f32_16x16x32_bf16 v[72:75], v[172:175], v[226:229], v[72:75]
	v_mfma_f32_16x16x32_bf16 v[68:71], v[180:183], v[226:229], v[68:71]
	s_barrier
	s_add_u32 s98, s8, s4
	s_addc_u32 s99, s9, s5
	s_add_i32 s62, s62, s12
	s_mov_b32 m0, s62
	ds_read_b128 v[184:187], v154 offset:16384
	ds_read_b128 v[188:191], v154 offset:17408
	ds_read_b128 v[192:195], v154 offset:18432
	ds_read_b128 v[202:205], v154 offset:19456
	ds_read_b128 v[214:217], v154 offset:20480
	ds_read_b128 v[218:221], v154 offset:21504
	ds_read_b128 v[222:225], v154 offset:22528
	ds_read_b128 v[226:229], v154 offset:23552
	global_load_lds_dwordx4 v2, s[6:7]
	s_add_i32 m0, s62, 0x2000
	s_add_u32 s62, s6, 0x4000
	s_addc_u32 s63, s7, 0
	s_add_i32 s64, s64, s12
	global_load_lds_dwordx4 v132, s[6:7]
	s_mov_b32 m0, s64
	s_nop 0
	global_load_lds_dwordx4 v2, s[62:63]
	s_add_i32 m0, s64, 0x2000
	s_nop 0
	global_load_lds_dwordx4 v132, s[62:63]
	s_mov_b32 m0, s13
	s_nop 0
	global_load_lds_dwordx4 v136, s[8:9]
	s_mov_b32 m0, s14
	s_nop 0
	global_load_lds_dwordx4 v134, s[8:9]
	s_waitcnt vmcnt(8)
	s_waitcnt lgkmcnt(0)
	s_barrier
	s_waitcnt lgkmcnt(0)
	v_mfma_f32_16x16x32_bf16 v[64:67], v[142:145], v[184:187], v[64:67]
	v_mfma_f32_16x16x32_bf16 v[60:63], v[160:163], v[184:187], v[60:63]
	v_mfma_f32_16x16x32_bf16 v[48:51], v[142:145], v[192:195], v[48:51]
	v_mfma_f32_16x16x32_bf16 v[44:47], v[160:163], v[192:195], v[44:47]
	v_mfma_f32_16x16x32_bf16 v[32:35], v[142:145], v[214:217], v[32:35]
	v_mfma_f32_16x16x32_bf16 v[28:31], v[160:163], v[214:217], v[28:31]
	v_mfma_f32_16x16x32_bf16 v[16:19], v[142:145], v[222:225], v[16:19]
	v_mfma_f32_16x16x32_bf16 v[12:15], v[160:163], v[222:225], v[12:15]
	v_mfma_f32_16x16x32_bf16 v[64:67], v[156:159], v[188:191], v[64:67]
	v_mfma_f32_16x16x32_bf16 v[60:63], v[164:167], v[188:191], v[60:63]
	v_mfma_f32_16x16x32_bf16 v[48:51], v[156:159], v[202:205], v[48:51]
	v_mfma_f32_16x16x32_bf16 v[44:47], v[164:167], v[202:205], v[44:47]
	v_mfma_f32_16x16x32_bf16 v[32:35], v[156:159], v[218:221], v[32:35]
	v_mfma_f32_16x16x32_bf16 v[28:31], v[164:167], v[218:221], v[28:31]
	v_mfma_f32_16x16x32_bf16 v[16:19], v[156:159], v[226:229], v[16:19]
	v_mfma_f32_16x16x32_bf16 v[12:15], v[164:167], v[226:229], v[12:15]
	v_mfma_f32_16x16x32_bf16 v[56:59], v[168:171], v[184:187], v[56:59]
	v_mfma_f32_16x16x32_bf16 v[52:55], v[176:179], v[184:187], v[52:55]
	v_mfma_f32_16x16x32_bf16 v[40:43], v[168:171], v[192:195], v[40:43]
	v_mfma_f32_16x16x32_bf16 v[36:39], v[176:179], v[192:195], v[36:39]
	v_mfma_f32_16x16x32_bf16 v[24:27], v[168:171], v[214:217], v[24:27]
	v_mfma_f32_16x16x32_bf16 v[20:23], v[176:179], v[214:217], v[20:23]
	v_mfma_f32_16x16x32_bf16 v[8:11], v[168:171], v[222:225], v[8:11]
	v_mfma_f32_16x16x32_bf16 v[4:7], v[176:179], v[222:225], v[4:7]
	v_mfma_f32_16x16x32_bf16 v[56:59], v[172:175], v[188:191], v[56:59]
	v_mfma_f32_16x16x32_bf16 v[52:55], v[180:183], v[188:191], v[52:55]
	v_mfma_f32_16x16x32_bf16 v[40:43], v[172:175], v[202:205], v[40:43]
	v_mfma_f32_16x16x32_bf16 v[36:39], v[180:183], v[202:205], v[36:39]
	v_mfma_f32_16x16x32_bf16 v[24:27], v[172:175], v[218:221], v[24:27]
	v_mfma_f32_16x16x32_bf16 v[20:23], v[180:183], v[218:221], v[20:23]
	v_mfma_f32_16x16x32_bf16 v[8:11], v[172:175], v[226:229], v[8:11]
	v_mfma_f32_16x16x32_bf16 v[4:7], v[180:183], v[226:229], v[4:7]
	s_barrier
	s_add_i32 s62, 0, 0x18000
	s_add_i32 s63, 0, 0x1c000
	ds_read_b128 v[142:145], v230 offset:32768
	ds_read_b128 v[156:159], v230 offset:33792
	ds_read_b128 v[160:163], v230 offset:34816
	ds_read_b128 v[164:167], v230 offset:35840
	ds_read_b128 v[168:171], v230 offset:49152
	ds_read_b128 v[172:175], v230 offset:50176
	ds_read_b128 v[176:179], v230 offset:51200
	ds_read_b128 v[180:183], v230 offset:52224
	s_add_u32 s8, s8, 0x80000
	s_addc_u32 s9, s9, 0
	s_mov_b32 m0, s15
	ds_read_b128 v[184:187], v154 offset:32768
	ds_read_b128 v[188:191], v154 offset:33792
	ds_read_b128 v[192:195], v154 offset:34816
	ds_read_b128 v[202:205], v154 offset:35840
	ds_read_b128 v[214:217], v154 offset:36864
	ds_read_b128 v[218:221], v154 offset:37888
	ds_read_b128 v[222:225], v154 offset:38912
	ds_read_b128 v[226:229], v154 offset:39936
	global_load_lds_dwordx4 v136, s[8:9]
	s_mov_b32 m0, s22
	s_nop 0
	global_load_lds_dwordx4 v134, s[8:9]
	s_waitcnt vmcnt(8)
	s_waitcnt lgkmcnt(0)
	s_barrier
	s_waitcnt lgkmcnt(0)
	v_mfma_f32_16x16x32_bf16 v[128:131], v[142:145], v[184:187], v[128:131]
	v_mfma_f32_16x16x32_bf16 v[124:127], v[160:163], v[184:187], v[124:127]
	v_mfma_f32_16x16x32_bf16 v[112:115], v[142:145], v[192:195], v[112:115]
	v_mfma_f32_16x16x32_bf16 v[108:111], v[160:163], v[192:195], v[108:111]
	v_mfma_f32_16x16x32_bf16 v[96:99], v[142:145], v[214:217], v[96:99]
	v_mfma_f32_16x16x32_bf16 v[92:95], v[160:163], v[214:217], v[92:95]
	v_mfma_f32_16x16x32_bf16 v[80:83], v[142:145], v[222:225], v[80:83]
	v_mfma_f32_16x16x32_bf16 v[76:79], v[160:163], v[222:225], v[76:79]
	v_mfma_f32_16x16x32_bf16 v[128:131], v[156:159], v[188:191], v[128:131]
	v_mfma_f32_16x16x32_bf16 v[124:127], v[164:167], v[188:191], v[124:127]
	v_mfma_f32_16x16x32_bf16 v[112:115], v[156:159], v[202:205], v[112:115]
	v_mfma_f32_16x16x32_bf16 v[108:111], v[164:167], v[202:205], v[108:111]
	v_mfma_f32_16x16x32_bf16 v[96:99], v[156:159], v[218:221], v[96:99]
	v_mfma_f32_16x16x32_bf16 v[92:95], v[164:167], v[218:221], v[92:95]
	v_mfma_f32_16x16x32_bf16 v[80:83], v[156:159], v[226:229], v[80:83]
	v_mfma_f32_16x16x32_bf16 v[76:79], v[164:167], v[226:229], v[76:79]
	v_mfma_f32_16x16x32_bf16 v[120:123], v[168:171], v[184:187], v[120:123]
	v_mfma_f32_16x16x32_bf16 v[116:119], v[176:179], v[184:187], v[116:119]
	v_mfma_f32_16x16x32_bf16 v[104:107], v[168:171], v[192:195], v[104:107]
	v_mfma_f32_16x16x32_bf16 v[100:103], v[176:179], v[192:195], v[100:103]
	v_mfma_f32_16x16x32_bf16 v[88:91], v[168:171], v[214:217], v[88:91]
	v_mfma_f32_16x16x32_bf16 v[84:87], v[176:179], v[214:217], v[84:87]
	v_mfma_f32_16x16x32_bf16 v[72:75], v[168:171], v[222:225], v[72:75]
	v_mfma_f32_16x16x32_bf16 v[68:71], v[176:179], v[222:225], v[68:71]
	v_mfma_f32_16x16x32_bf16 v[120:123], v[172:175], v[188:191], v[120:123]
	v_mfma_f32_16x16x32_bf16 v[116:119], v[180:183], v[188:191], v[116:119]
	v_mfma_f32_16x16x32_bf16 v[104:107], v[172:175], v[202:205], v[104:107]
	v_mfma_f32_16x16x32_bf16 v[100:103], v[180:183], v[202:205], v[100:103]
	v_mfma_f32_16x16x32_bf16 v[88:91], v[172:175], v[218:221], v[88:91]
	v_mfma_f32_16x16x32_bf16 v[84:87], v[180:183], v[218:221], v[84:87]
	v_mfma_f32_16x16x32_bf16 v[72:75], v[172:175], v[226:229], v[72:75]
	v_mfma_f32_16x16x32_bf16 v[68:71], v[180:183], v[226:229], v[68:71]
	s_barrier
	s_add_u32 s8, s6, 0x8000
	s_addc_u32 s9, s7, 0
	s_add_i32 s62, s62, s12
	s_mov_b32 m0, s62
	ds_read_b128 v[184:187], v154 offset:49152
	ds_read_b128 v[188:191], v154 offset:50176
	ds_read_b128 v[192:195], v154 offset:51200
	ds_read_b128 v[202:205], v154 offset:52224
	ds_read_b128 v[214:217], v154 offset:53248
	ds_read_b128 v[218:221], v154 offset:54272
	ds_read_b128 v[222:225], v154 offset:55296
	ds_read_b128 v[226:229], v154 offset:56320
	global_load_lds_dwordx4 v2, s[8:9]
	s_add_i32 m0, s62, 0x2000
	s_add_u32 s6, s6, 0xc000
	s_addc_u32 s7, s7, 0
	global_load_lds_dwordx4 v132, s[8:9]
	s_add_i32 s8, s63, s12
	s_mov_b32 m0, s8
	s_nop 0
	global_load_lds_dwordx4 v2, s[6:7]
	s_add_i32 m0, s8, 0x2000
	s_nop 0
	global_load_lds_dwordx4 v132, s[6:7]
	s_mov_b32 m0, s34
	s_nop 0
	global_load_lds_dwordx4 v136, s[98:99]
	s_mov_b32 m0, s35
	s_nop 0
	global_load_lds_dwordx4 v134, s[98:99]
	s_waitcnt vmcnt(8)
	s_waitcnt lgkmcnt(0)
	s_barrier
	s_waitcnt lgkmcnt(0)
	v_mfma_f32_16x16x32_bf16 v[64:67], v[142:145], v[184:187], v[64:67]
	v_mfma_f32_16x16x32_bf16 v[60:63], v[160:163], v[184:187], v[60:63]
	v_mfma_f32_16x16x32_bf16 v[48:51], v[142:145], v[192:195], v[48:51]
	v_mfma_f32_16x16x32_bf16 v[44:47], v[160:163], v[192:195], v[44:47]
	v_mfma_f32_16x16x32_bf16 v[32:35], v[142:145], v[214:217], v[32:35]
	v_mfma_f32_16x16x32_bf16 v[28:31], v[160:163], v[214:217], v[28:31]
	v_mfma_f32_16x16x32_bf16 v[16:19], v[142:145], v[222:225], v[16:19]
	v_mfma_f32_16x16x32_bf16 v[12:15], v[160:163], v[222:225], v[12:15]
	v_mfma_f32_16x16x32_bf16 v[64:67], v[156:159], v[188:191], v[64:67]
	v_mfma_f32_16x16x32_bf16 v[60:63], v[164:167], v[188:191], v[60:63]
	v_mfma_f32_16x16x32_bf16 v[48:51], v[156:159], v[202:205], v[48:51]
	v_mfma_f32_16x16x32_bf16 v[44:47], v[164:167], v[202:205], v[44:47]
	v_mfma_f32_16x16x32_bf16 v[32:35], v[156:159], v[218:221], v[32:35]
	v_mfma_f32_16x16x32_bf16 v[28:31], v[164:167], v[218:221], v[28:31]
	v_mfma_f32_16x16x32_bf16 v[16:19], v[156:159], v[226:229], v[16:19]
	v_mfma_f32_16x16x32_bf16 v[12:15], v[164:167], v[226:229], v[12:15]
	v_mfma_f32_16x16x32_bf16 v[56:59], v[168:171], v[184:187], v[56:59]
	v_mfma_f32_16x16x32_bf16 v[52:55], v[176:179], v[184:187], v[52:55]
	v_mfma_f32_16x16x32_bf16 v[40:43], v[168:171], v[192:195], v[40:43]
	v_mfma_f32_16x16x32_bf16 v[36:39], v[176:179], v[192:195], v[36:39]
	v_mfma_f32_16x16x32_bf16 v[24:27], v[168:171], v[214:217], v[24:27]
	v_mfma_f32_16x16x32_bf16 v[20:23], v[176:179], v[214:217], v[20:23]
	v_mfma_f32_16x16x32_bf16 v[8:11], v[168:171], v[222:225], v[8:11]
	v_mfma_f32_16x16x32_bf16 v[4:7], v[176:179], v[222:225], v[4:7]
	v_mfma_f32_16x16x32_bf16 v[56:59], v[172:175], v[188:191], v[56:59]
	v_mfma_f32_16x16x32_bf16 v[52:55], v[180:183], v[188:191], v[52:55]
	v_mfma_f32_16x16x32_bf16 v[40:43], v[172:175], v[202:205], v[40:43]
	v_mfma_f32_16x16x32_bf16 v[36:39], v[180:183], v[202:205], v[36:39]
	v_mfma_f32_16x16x32_bf16 v[24:27], v[172:175], v[218:221], v[24:27]
	v_mfma_f32_16x16x32_bf16 v[20:23], v[180:183], v[218:221], v[20:23]
	v_mfma_f32_16x16x32_bf16 v[8:11], v[172:175], v[226:229], v[8:11]
	v_mfma_f32_16x16x32_bf16 v[4:7], v[180:183], v[226:229], v[4:7]
	s_barrier
	s_add_i32 s61, s61, 2
	s_add_u32 s59, s59, 0x10000
	s_addc_u32 s60, s60, 0
	s_add_u32 s0, s0, 0x100
	s_addc_u32 s1, s1, 0
	s_cmp_gt_u32 s61, 29
	s_cbranch_scc0 .LBB0_366
	s_and_b64 vcc, exec, s[46:47]
	s_cbranch_vccz .LBB0_369
	s_barrier

.LBB0_732:
	s_ashr_i32 s13, s12, 31
	s_lshl_b64 s[14:15], s[12:13], 20
	s_add_u32 s14, s92, s14
	s_addc_u32 s15, s93, s15
	s_and_b64 s[22:23], s[46:47], exec
	s_cselect_b32 s13, s15, s49
	s_cselect_b32 s64, s14, s48
	s_ashr_i32 s9, s8, 31
	s_lshl_b64 s[22:23], s[8:9], 20
	s_add_u32 s22, s53, s22
	s_addc_u32 s23, s54, s23
	s_and_b64 s[50:51], s[46:47], exec
	s_cselect_b32 s9, s23, s35
	s_cselect_b32 s65, s22, s34
	s_add_u32 s66, s34, 0x10000
	s_addc_u32 s67, s35, 0
	s_add_u32 s34, s48, 0x80080
	v_mov_b32_e32 v4, 0
	s_addc_u32 s35, s49, 0
	s_mov_b32 s68, -2
	v_mov_b32_e32 v5, v4
	v_mov_b32_e32 v6, v4
	v_mov_b32_e32 v7, v4
	v_mov_b32_e32 v8, v4
	v_mov_b32_e32 v9, v4
	v_mov_b32_e32 v10, v4
	v_mov_b32_e32 v11, v4
	v_mov_b32_e32 v20, v4
	v_mov_b32_e32 v21, v4
	v_mov_b32_e32 v22, v4
	v_mov_b32_e32 v23, v4
	v_mov_b32_e32 v24, v4
	v_mov_b32_e32 v25, v4
	v_mov_b32_e32 v26, v4
	v_mov_b32_e32 v27, v4
	v_mov_b32_e32 v36, v4
	v_mov_b32_e32 v37, v4
	v_mov_b32_e32 v38, v4
	v_mov_b32_e32 v39, v4
	v_mov_b32_e32 v40, v4
	v_mov_b32_e32 v41, v4
	v_mov_b32_e32 v42, v4
	v_mov_b32_e32 v43, v4
	v_mov_b32_e32 v52, v4
	v_mov_b32_e32 v53, v4
	v_mov_b32_e32 v54, v4
	v_mov_b32_e32 v55, v4
	v_mov_b32_e32 v56, v4
	v_mov_b32_e32 v57, v4
	v_mov_b32_e32 v58, v4
	v_mov_b32_e32 v59, v4
	v_mov_b32_e32 v12, v4
	v_mov_b32_e32 v13, v4
	v_mov_b32_e32 v14, v4
	v_mov_b32_e32 v15, v4
	v_mov_b32_e32 v16, v4
	v_mov_b32_e32 v17, v4
	v_mov_b32_e32 v18, v4
	v_mov_b32_e32 v19, v4
	v_mov_b32_e32 v28, v4
	v_mov_b32_e32 v29, v4
	v_mov_b32_e32 v30, v4
	v_mov_b32_e32 v31, v4
	v_mov_b32_e32 v32, v4
	v_mov_b32_e32 v33, v4
	v_mov_b32_e32 v34, v4
	v_mov_b32_e32 v35, v4
	v_mov_b32_e32 v44, v4
	v_mov_b32_e32 v45, v4
	v_mov_b32_e32 v46, v4
	v_mov_b32_e32 v47, v4
	v_mov_b32_e32 v48, v4
	v_mov_b32_e32 v49, v4
	v_mov_b32_e32 v50, v4
	v_mov_b32_e32 v51, v4
	v_mov_b32_e32 v60, v4
	v_mov_b32_e32 v61, v4
	v_mov_b32_e32 v62, v4
	v_mov_b32_e32 v63, v4
	v_mov_b32_e32 v64, v4
	v_mov_b32_e32 v65, v4
	v_mov_b32_e32 v66, v4
	v_mov_b32_e32 v67, v4
	v_mov_b32_e32 v68, v4
	v_mov_b32_e32 v69, v4
	v_mov_b32_e32 v70, v4
	v_mov_b32_e32 v71, v4
	v_mov_b32_e32 v72, v4
	v_mov_b32_e32 v73, v4
	v_mov_b32_e32 v74, v4
	v_mov_b32_e32 v75, v4
	v_mov_b32_e32 v84, v4
	v_mov_b32_e32 v85, v4
	v_mov_b32_e32 v86, v4
	v_mov_b32_e32 v87, v4
	v_mov_b32_e32 v88, v4
	v_mov_b32_e32 v89, v4
	v_mov_b32_e32 v90, v4
	v_mov_b32_e32 v91, v4
	v_mov_b32_e32 v100, v4
	v_mov_b32_e32 v101, v4
	v_mov_b32_e32 v102, v4
	v_mov_b32_e32 v103, v4
	v_mov_b32_e32 v104, v4
	v_mov_b32_e32 v105, v4
	v_mov_b32_e32 v106, v4
	v_mov_b32_e32 v107, v4
	v_mov_b32_e32 v120, v4
	v_mov_b32_e32 v121, v4
	v_mov_b32_e32 v122, v4
	v_mov_b32_e32 v123, v4
	v_mov_b32_e32 v124, v4
	v_mov_b32_e32 v125, v4
	v_mov_b32_e32 v126, v4
	v_mov_b32_e32 v127, v4
	v_mov_b32_e32 v76, v4
	v_mov_b32_e32 v77, v4
	v_mov_b32_e32 v78, v4
	v_mov_b32_e32 v79, v4
	v_mov_b32_e32 v80, v4
	v_mov_b32_e32 v81, v4
	v_mov_b32_e32 v82, v4
	v_mov_b32_e32 v83, v4
	v_mov_b32_e32 v92, v4
	v_mov_b32_e32 v93, v4
	v_mov_b32_e32 v94, v4
	v_mov_b32_e32 v95, v4
	v_mov_b32_e32 v96, v4
	v_mov_b32_e32 v97, v4
	v_mov_b32_e32 v98, v4
	v_mov_b32_e32 v99, v4
	v_mov_b32_e32 v108, v4
	v_mov_b32_e32 v109, v4
	v_mov_b32_e32 v110, v4
	v_mov_b32_e32 v111, v4
	v_mov_b32_e32 v112, v4
	v_mov_b32_e32 v113, v4
	v_mov_b32_e32 v114, v4
	v_mov_b32_e32 v115, v4
	v_mov_b32_e32 v144, v4
	v_mov_b32_e32 v145, v4
	v_mov_b32_e32 v146, v4
	v_mov_b32_e32 v147, v4
	v_mov_b32_e32 v156, v4
	v_mov_b32_e32 v157, v4
	v_mov_b32_e32 v158, v4
	v_mov_b32_e32 v159, v4
	v_add_u32_e32 v224, 0x10000, v204
.LBB0_733:
	s_add_u32 s48, s34, 0xfff80080
	s_addc_u32 s49, s35, -1
	s_add_i32 s69, 0, 0x10000
	s_cmp_eq_u32 s68, 28
	s_cselect_b32 s51, s13, s49
	s_cselect_b32 s50, s64, s48
	s_cselect_b32 s49, s9, s67
	s_cselect_b32 s48, s65, s66
	s_add_i32 s72, 0, 0x14000
	ds_read_b128 v[116:119], v224
	ds_read_b128 v[128:131], v224 offset:1024
	ds_read_b128 v[132:135], v224 offset:2048
	ds_read_b128 v[136:139], v224 offset:3072
	ds_read_b128 v[140:143], v224 offset:16384
	ds_read_b128 v[148:151], v224 offset:17408
	ds_read_b128 v[152:155], v224 offset:18432
	ds_read_b128 v[160:163], v224 offset:19456
	s_add_i32 m0, s55, 0xc000
	ds_read_b128 v[164:167], v244
	ds_read_b128 v[168:171], v244 offset:1024
	ds_read_b128 v[172:175], v244 offset:2048
	ds_read_b128 v[176:179], v244 offset:3072
	ds_read_b128 v[180:183], v244 offset:4096
	ds_read_b128 v[184:187], v244 offset:5120
	ds_read_b128 v[188:191], v244 offset:6144
	ds_read_b128 v[192:195], v244 offset:7168
	global_load_lds_dwordx4 v218, s[34:35]
	s_add_i32 m0, s55, 0xe000
	s_nop 0
	global_load_lds_dwordx4 v220, s[34:35]
	s_waitcnt vmcnt(8)
	s_waitcnt lgkmcnt(0)
	s_barrier
	s_waitcnt lgkmcnt(0)
	v_mfma_f32_16x16x32_bf16 v[156:159], v[116:119], v[164:167], v[156:159]
	v_mfma_f32_16x16x32_bf16 v[144:147], v[132:135], v[164:167], v[144:147]
	v_mfma_f32_16x16x32_bf16 v[112:115], v[116:119], v[172:175], v[112:115]
	v_mfma_f32_16x16x32_bf16 v[108:111], v[132:135], v[172:175], v[108:111]
	v_mfma_f32_16x16x32_bf16 v[96:99], v[116:119], v[180:183], v[96:99]
	v_mfma_f32_16x16x32_bf16 v[92:95], v[132:135], v[180:183], v[92:95]
	v_mfma_f32_16x16x32_bf16 v[80:83], v[116:119], v[188:191], v[80:83]
	v_mfma_f32_16x16x32_bf16 v[76:79], v[132:135], v[188:191], v[76:79]
	v_mfma_f32_16x16x32_bf16 v[156:159], v[128:131], v[168:171], v[156:159]
	v_mfma_f32_16x16x32_bf16 v[144:147], v[136:139], v[168:171], v[144:147]
	v_mfma_f32_16x16x32_bf16 v[112:115], v[128:131], v[176:179], v[112:115]
	v_mfma_f32_16x16x32_bf16 v[108:111], v[136:139], v[176:179], v[108:111]
	v_mfma_f32_16x16x32_bf16 v[96:99], v[128:131], v[184:187], v[96:99]
	v_mfma_f32_16x16x32_bf16 v[92:95], v[136:139], v[184:187], v[92:95]
	v_mfma_f32_16x16x32_bf16 v[80:83], v[128:131], v[192:195], v[80:83]
	v_mfma_f32_16x16x32_bf16 v[76:79], v[136:139], v[192:195], v[76:79]
	v_mfma_f32_16x16x32_bf16 v[124:127], v[140:143], v[164:167], v[124:127]
	v_mfma_f32_16x16x32_bf16 v[120:123], v[152:155], v[164:167], v[120:123]
	v_mfma_f32_16x16x32_bf16 v[104:107], v[140:143], v[172:175], v[104:107]
	v_mfma_f32_16x16x32_bf16 v[100:103], v[152:155], v[172:175], v[100:103]
	v_mfma_f32_16x16x32_bf16 v[88:91], v[140:143], v[180:183], v[88:91]
	v_mfma_f32_16x16x32_bf16 v[84:87], v[152:155], v[180:183], v[84:87]
	v_mfma_f32_16x16x32_bf16 v[72:75], v[140:143], v[188:191], v[72:75]
	v_mfma_f32_16x16x32_bf16 v[68:71], v[152:155], v[188:191], v[68:71]
	v_mfma_f32_16x16x32_bf16 v[124:127], v[148:151], v[168:171], v[124:127]
	v_mfma_f32_16x16x32_bf16 v[120:123], v[160:163], v[168:171], v[120:123]
	v_mfma_f32_16x16x32_bf16 v[104:107], v[148:151], v[176:179], v[104:107]
	v_mfma_f32_16x16x32_bf16 v[100:103], v[160:163], v[176:179], v[100:103]
	v_mfma_f32_16x16x32_bf16 v[88:91], v[148:151], v[184:187], v[88:91]
	v_mfma_f32_16x16x32_bf16 v[84:87], v[160:163], v[184:187], v[84:87]
	v_mfma_f32_16x16x32_bf16 v[72:75], v[148:151], v[192:195], v[72:75]
	v_mfma_f32_16x16x32_bf16 v[68:71], v[160:163], v[192:195], v[68:71]
	s_barrier
	s_add_u32 s98, s50, s4
	s_addc_u32 s99, s51, s5
	s_add_i32 s69, s69, s52
	s_mov_b32 m0, s69
	ds_read_b128 v[164:167], v244 offset:16384
	ds_read_b128 v[168:171], v244 offset:17408
	ds_read_b128 v[172:175], v244 offset:18432
	ds_read_b128 v[176:179], v244 offset:19456
	ds_read_b128 v[180:183], v244 offset:20480
	ds_read_b128 v[184:187], v244 offset:21504
	ds_read_b128 v[188:191], v244 offset:22528
	ds_read_b128 v[192:195], v244 offset:23552
	global_load_lds_dwordx4 v2, s[48:49]
	s_add_i32 m0, s69, 0x2000
	s_add_u32 s70, s48, 0x4000
	s_addc_u32 s71, s49, 0
	s_add_i32 s69, s72, s52
	global_load_lds_dwordx4 v196, s[48:49]
	s_mov_b32 m0, s69
	s_nop 0
	global_load_lds_dwordx4 v2, s[70:71]
	s_add_i32 m0, s69, 0x2000
	s_nop 0
	global_load_lds_dwordx4 v196, s[70:71]
	s_mov_b32 m0, s55
	s_nop 0
	global_load_lds_dwordx4 v216, s[50:51]
	s_mov_b32 m0, s56
	s_nop 0
	global_load_lds_dwordx4 v214, s[50:51]
	s_waitcnt vmcnt(8)
	s_waitcnt lgkmcnt(0)
	s_barrier
	s_waitcnt lgkmcnt(0)
	v_mfma_f32_16x16x32_bf16 v[64:67], v[116:119], v[164:167], v[64:67]
	v_mfma_f32_16x16x32_bf16 v[60:63], v[132:135], v[164:167], v[60:63]
	v_mfma_f32_16x16x32_bf16 v[48:51], v[116:119], v[172:175], v[48:51]
	v_mfma_f32_16x16x32_bf16 v[44:47], v[132:135], v[172:175], v[44:47]
	v_mfma_f32_16x16x32_bf16 v[32:35], v[116:119], v[180:183], v[32:35]
	v_mfma_f32_16x16x32_bf16 v[28:31], v[132:135], v[180:183], v[28:31]
	v_mfma_f32_16x16x32_bf16 v[16:19], v[116:119], v[188:191], v[16:19]
	v_mfma_f32_16x16x32_bf16 v[12:15], v[132:135], v[188:191], v[12:15]
	v_mfma_f32_16x16x32_bf16 v[64:67], v[128:131], v[168:171], v[64:67]
	v_mfma_f32_16x16x32_bf16 v[60:63], v[136:139], v[168:171], v[60:63]
	v_mfma_f32_16x16x32_bf16 v[48:51], v[128:131], v[176:179], v[48:51]
	v_mfma_f32_16x16x32_bf16 v[44:47], v[136:139], v[176:179], v[44:47]
	v_mfma_f32_16x16x32_bf16 v[32:35], v[128:131], v[184:187], v[32:35]
	v_mfma_f32_16x16x32_bf16 v[28:31], v[136:139], v[184:187], v[28:31]
	v_mfma_f32_16x16x32_bf16 v[16:19], v[128:131], v[192:195], v[16:19]
	v_mfma_f32_16x16x32_bf16 v[12:15], v[136:139], v[192:195], v[12:15]
	v_mfma_f32_16x16x32_bf16 v[56:59], v[140:143], v[164:167], v[56:59]
	v_mfma_f32_16x16x32_bf16 v[52:55], v[152:155], v[164:167], v[52:55]
	v_mfma_f32_16x16x32_bf16 v[40:43], v[140:143], v[172:175], v[40:43]
	v_mfma_f32_16x16x32_bf16 v[36:39], v[152:155], v[172:175], v[36:39]
	v_mfma_f32_16x16x32_bf16 v[24:27], v[140:143], v[180:183], v[24:27]
	v_mfma_f32_16x16x32_bf16 v[20:23], v[152:155], v[180:183], v[20:23]
	v_mfma_f32_16x16x32_bf16 v[8:11], v[140:143], v[188:191], v[8:11]
	v_mfma_f32_16x16x32_bf16 v[4:7], v[152:155], v[188:191], v[4:7]
	v_mfma_f32_16x16x32_bf16 v[56:59], v[148:151], v[168:171], v[56:59]
	v_mfma_f32_16x16x32_bf16 v[52:55], v[160:163], v[168:171], v[52:55]
	v_mfma_f32_16x16x32_bf16 v[40:43], v[148:151], v[176:179], v[40:43]
	v_mfma_f32_16x16x32_bf16 v[36:39], v[160:163], v[176:179], v[36:39]
	v_mfma_f32_16x16x32_bf16 v[24:27], v[148:151], v[184:187], v[24:27]
	v_mfma_f32_16x16x32_bf16 v[20:23], v[160:163], v[184:187], v[20:23]
	v_mfma_f32_16x16x32_bf16 v[8:11], v[148:151], v[192:195], v[8:11]
	v_mfma_f32_16x16x32_bf16 v[4:7], v[160:163], v[192:195], v[4:7]
	s_barrier
	s_add_i32 s69, 0, 0x18000
	s_add_i32 s70, 0, 0x1c000
	ds_read_b128 v[116:119], v224 offset:32768
	ds_read_b128 v[128:131], v224 offset:33792
	ds_read_b128 v[132:135], v224 offset:34816
	ds_read_b128 v[136:139], v224 offset:35840
	ds_read_b128 v[140:143], v224 offset:49152
	ds_read_b128 v[148:151], v224 offset:50176
	ds_read_b128 v[152:155], v224 offset:51200
	ds_read_b128 v[160:163], v224 offset:52224
	s_add_u32 s50, s50, 0x80000
	s_addc_u32 s51, s51, 0
	s_mov_b32 m0, s57
	ds_read_b128 v[164:167], v244 offset:32768
	ds_read_b128 v[168:171], v244 offset:33792
	ds_read_b128 v[172:175], v244 offset:34816
	ds_read_b128 v[176:179], v244 offset:35840
	ds_read_b128 v[180:183], v244 offset:36864
	ds_read_b128 v[184:187], v244 offset:37888
	ds_read_b128 v[188:191], v244 offset:38912
	ds_read_b128 v[192:195], v244 offset:39936
	global_load_lds_dwordx4 v216, s[50:51]
	s_mov_b32 m0, s58
	s_nop 0
	global_load_lds_dwordx4 v214, s[50:51]
	s_waitcnt vmcnt(8)
	s_waitcnt lgkmcnt(0)
	s_barrier
	s_waitcnt lgkmcnt(0)
	v_mfma_f32_16x16x32_bf16 v[156:159], v[116:119], v[164:167], v[156:159]
	v_mfma_f32_16x16x32_bf16 v[144:147], v[132:135], v[164:167], v[144:147]
	v_mfma_f32_16x16x32_bf16 v[112:115], v[116:119], v[172:175], v[112:115]
	v_mfma_f32_16x16x32_bf16 v[108:111], v[132:135], v[172:175], v[108:111]
	v_mfma_f32_16x16x32_bf16 v[96:99], v[116:119], v[180:183], v[96:99]
	v_mfma_f32_16x16x32_bf16 v[92:95], v[132:135], v[180:183], v[92:95]
	v_mfma_f32_16x16x32_bf16 v[80:83], v[116:119], v[188:191], v[80:83]
	v_mfma_f32_16x16x32_bf16 v[76:79], v[132:135], v[188:191], v[76:79]
	v_mfma_f32_16x16x32_bf16 v[156:159], v[128:131], v[168:171], v[156:159]
	v_mfma_f32_16x16x32_bf16 v[144:147], v[136:139], v[168:171], v[144:147]
	v_mfma_f32_16x16x32_bf16 v[112:115], v[128:131], v[176:179], v[112:115]
	v_mfma_f32_16x16x32_bf16 v[108:111], v[136:139], v[176:179], v[108:111]
	v_mfma_f32_16x16x32_bf16 v[96:99], v[128:131], v[184:187], v[96:99]
	v_mfma_f32_16x16x32_bf16 v[92:95], v[136:139], v[184:187], v[92:95]
	v_mfma_f32_16x16x32_bf16 v[80:83], v[128:131], v[192:195], v[80:83]
	v_mfma_f32_16x16x32_bf16 v[76:79], v[136:139], v[192:195], v[76:79]
	v_mfma_f32_16x16x32_bf16 v[124:127], v[140:143], v[164:167], v[124:127]
	v_mfma_f32_16x16x32_bf16 v[120:123], v[152:155], v[164:167], v[120:123]
	v_mfma_f32_16x16x32_bf16 v[104:107], v[140:143], v[172:175], v[104:107]
	v_mfma_f32_16x16x32_bf16 v[100:103], v[152:155], v[172:175], v[100:103]
	v_mfma_f32_16x16x32_bf16 v[88:91], v[140:143], v[180:183], v[88:91]
	v_mfma_f32_16x16x32_bf16 v[84:87], v[152:155], v[180:183], v[84:87]
	v_mfma_f32_16x16x32_bf16 v[72:75], v[140:143], v[188:191], v[72:75]
	v_mfma_f32_16x16x32_bf16 v[68:71], v[152:155], v[188:191], v[68:71]
	v_mfma_f32_16x16x32_bf16 v[124:127], v[148:151], v[168:171], v[124:127]
	v_mfma_f32_16x16x32_bf16 v[120:123], v[160:163], v[168:171], v[120:123]
	v_mfma_f32_16x16x32_bf16 v[104:107], v[148:151], v[176:179], v[104:107]
	v_mfma_f32_16x16x32_bf16 v[100:103], v[160:163], v[176:179], v[100:103]
	v_mfma_f32_16x16x32_bf16 v[88:91], v[148:151], v[184:187], v[88:91]
	v_mfma_f32_16x16x32_bf16 v[84:87], v[160:163], v[184:187], v[84:87]
	v_mfma_f32_16x16x32_bf16 v[72:75], v[148:151], v[192:195], v[72:75]
	v_mfma_f32_16x16x32_bf16 v[68:71], v[160:163], v[192:195], v[68:71]
	s_barrier
	s_add_u32 s50, s48, 0x8000
	s_addc_u32 s51, s49, 0
	s_add_i32 s69, s69, s52
	s_mov_b32 m0, s69
	ds_read_b128 v[164:167], v244 offset:49152
	ds_read_b128 v[168:171], v244 offset:50176
	ds_read_b128 v[172:175], v244 offset:51200
	ds_read_b128 v[176:179], v244 offset:52224
	ds_read_b128 v[180:183], v244 offset:53248
	ds_read_b128 v[184:187], v244 offset:54272
	ds_read_b128 v[188:191], v244 offset:55296
	ds_read_b128 v[192:195], v244 offset:56320
	global_load_lds_dwordx4 v2, s[50:51]
	s_add_i32 m0, s69, 0x2000
	s_add_u32 s48, s48, 0xc000
	s_addc_u32 s49, s49, 0
	global_load_lds_dwordx4 v196, s[50:51]
	s_add_i32 s50, s70, s52
	s_mov_b32 m0, s50
	s_nop 0
	global_load_lds_dwordx4 v2, s[48:49]
	s_add_i32 m0, s50, 0x2000
	s_nop 0
	global_load_lds_dwordx4 v196, s[48:49]
	s_mov_b32 m0, s59
	s_nop 0
	global_load_lds_dwordx4 v216, s[98:99]
	s_mov_b32 m0, s60
	s_nop 0
	global_load_lds_dwordx4 v214, s[98:99]
	s_waitcnt vmcnt(8)
	s_waitcnt lgkmcnt(0)
	s_barrier
	s_waitcnt lgkmcnt(0)
	v_mfma_f32_16x16x32_bf16 v[64:67], v[116:119], v[164:167], v[64:67]
	v_mfma_f32_16x16x32_bf16 v[60:63], v[132:135], v[164:167], v[60:63]
	v_mfma_f32_16x16x32_bf16 v[48:51], v[116:119], v[172:175], v[48:51]
	v_mfma_f32_16x16x32_bf16 v[44:47], v[132:135], v[172:175], v[44:47]
	v_mfma_f32_16x16x32_bf16 v[32:35], v[116:119], v[180:183], v[32:35]
	v_mfma_f32_16x16x32_bf16 v[28:31], v[132:135], v[180:183], v[28:31]
	v_mfma_f32_16x16x32_bf16 v[16:19], v[116:119], v[188:191], v[16:19]
	v_mfma_f32_16x16x32_bf16 v[12:15], v[132:135], v[188:191], v[12:15]
	v_mfma_f32_16x16x32_bf16 v[64:67], v[128:131], v[168:171], v[64:67]
	v_mfma_f32_16x16x32_bf16 v[60:63], v[136:139], v[168:171], v[60:63]
	v_mfma_f32_16x16x32_bf16 v[48:51], v[128:131], v[176:179], v[48:51]
	v_mfma_f32_16x16x32_bf16 v[44:47], v[136:139], v[176:179], v[44:47]
	v_mfma_f32_16x16x32_bf16 v[32:35], v[128:131], v[184:187], v[32:35]
	v_mfma_f32_16x16x32_bf16 v[28:31], v[136:139], v[184:187], v[28:31]
	v_mfma_f32_16x16x32_bf16 v[16:19], v[128:131], v[192:195], v[16:19]
	v_mfma_f32_16x16x32_bf16 v[12:15], v[136:139], v[192:195], v[12:15]
	v_mfma_f32_16x16x32_bf16 v[56:59], v[140:143], v[164:167], v[56:59]
	v_mfma_f32_16x16x32_bf16 v[52:55], v[152:155], v[164:167], v[52:55]
	v_mfma_f32_16x16x32_bf16 v[40:43], v[140:143], v[172:175], v[40:43]
	v_mfma_f32_16x16x32_bf16 v[36:39], v[152:155], v[172:175], v[36:39]
	v_mfma_f32_16x16x32_bf16 v[24:27], v[140:143], v[180:183], v[24:27]
	v_mfma_f32_16x16x32_bf16 v[20:23], v[152:155], v[180:183], v[20:23]
	v_mfma_f32_16x16x32_bf16 v[8:11], v[140:143], v[188:191], v[8:11]
	v_mfma_f32_16x16x32_bf16 v[4:7], v[152:155], v[188:191], v[4:7]
	v_mfma_f32_16x16x32_bf16 v[56:59], v[148:151], v[168:171], v[56:59]
	v_mfma_f32_16x16x32_bf16 v[52:55], v[160:163], v[168:171], v[52:55]
	v_mfma_f32_16x16x32_bf16 v[40:43], v[148:151], v[176:179], v[40:43]
	v_mfma_f32_16x16x32_bf16 v[36:39], v[160:163], v[176:179], v[36:39]
	v_mfma_f32_16x16x32_bf16 v[24:27], v[148:151], v[184:187], v[24:27]
	v_mfma_f32_16x16x32_bf16 v[20:23], v[160:163], v[184:187], v[20:23]
	v_mfma_f32_16x16x32_bf16 v[8:11], v[148:151], v[192:195], v[8:11]
	v_mfma_f32_16x16x32_bf16 v[4:7], v[160:163], v[192:195], v[4:7]
	s_barrier
	s_add_i32 s68, s68, 2
	s_add_u32 s66, s66, 0x10000
	s_addc_u32 s67, s67, 0
	s_add_u32 s34, s34, 0x100
	s_addc_u32 s35, s35, 0
	s_cmp_gt_u32 s68, 29
	s_cbranch_scc0 .LBB0_733
	s_and_b64 vcc, exec, s[6:7]
	s_cbranch_vccz .LBB0_736
	s_barrier

	.amdhsa_kernel _Z6mk_fwd4Args
		.amdhsa_group_segment_fixed_size 0
		.amdhsa_private_segment_fixed_size 0
		.amdhsa_kernarg_size 680
		.amdhsa_user_sgpr_count 2
		.amdhsa_user_sgpr_dispatch_ptr 0
		.amdhsa_user_sgpr_queue_ptr 0
		.amdhsa_user_sgpr_kernarg_segment_ptr 1
		.amdhsa_user_sgpr_dispatch_id 0
		.amdhsa_user_sgpr_kernarg_preload_length 0
		.amdhsa_user_sgpr_kernarg_preload_offset 0
		.amdhsa_user_sgpr_private_segment_size 0
		.amdhsa_uses_dynamic_stack 0
		.amdhsa_enable_private_segment 0
		.amdhsa_system_sgpr_workgroup_id_x 1
		.amdhsa_system_sgpr_workgroup_id_y 0
		.amdhsa_system_sgpr_workgroup_id_z 0
		.amdhsa_system_sgpr_workgroup_info 0
		.amdhsa_system_vgpr_workitem_id 0
		.amdhsa_next_free_vgpr 256
		.amdhsa_next_free_sgpr 102
		.amdhsa_accum_offset 256
		.amdhsa_reserve_vcc 1
		.amdhsa_float_round_mode_32 0
		.amdhsa_float_round_mode_16_64 0
		.amdhsa_float_denorm_mode_32 3
		.amdhsa_float_denorm_mode_16_64 3
		.amdhsa_dx10_clamp 1
		.amdhsa_ieee_mode 1
		.amdhsa_fp16_overflow 0
		.amdhsa_tg_split 0
		.amdhsa_exception_fp_ieee_invalid_op 0
		.amdhsa_exception_fp_denorm_src 0
		.amdhsa_exception_fp_ieee_div_zero 0
		.amdhsa_exception_fp_ieee_overflow 0
		.amdhsa_exception_fp_ieee_underflow 0
		.amdhsa_exception_fp_ieee_inexact 0
		.amdhsa_exception_int_div_zero 0
	.end_amdhsa_kernel

amdhsa.kernels:
  - .agpr_count:     0
    .args:
      - .offset:         0
        .size:           424
        .value_kind:     by_value
      - .offset:         424
        .size:           4
        .value_kind:     hidden_block_count_x
      - .offset:         428
        .size:           4
        .value_kind:     hidden_block_count_y
      - .offset:         432
        .size:           4
        .value_kind:     hidden_block_count_z
      - .offset:         436
        .size:           2
        .value_kind:     hidden_group_size_x
      - .offset:         438
        .size:           2
        .value_kind:     hidden_group_size_y
      - .offset:         440
        .size:           2
        .value_kind:     hidden_group_size_z
      - .offset:         442
        .size:           2
        .value_kind:     hidden_remainder_x
      - .offset:         444
        .size:           2
        .value_kind:     hidden_remainder_y
      - .offset:         446
        .size:           2
        .value_kind:     hidden_remainder_z
      - .offset:         464
        .size:           8
        .value_kind:     hidden_global_offset_x
      - .offset:         472
        .size:           8
        .value_kind:     hidden_global_offset_y
      - .offset:         480
        .size:           8
        .value_kind:     hidden_global_offset_z
      - .offset:         488
        .size:           2
        .value_kind:     hidden_grid_dims
      - .offset:         544
        .size:           4
        .value_kind:     hidden_dynamic_lds_size
    .group_segment_fixed_size: 0
    .kernarg_segment_align: 8
    .kernarg_segment_size: 680
    .language:       OpenCL C
    .language_version:
      - 2
      - 0
    .max_flat_workgroup_size: 512
    .name:           _Z6mk_fwd4Args
    .private_segment_fixed_size: 0
    .sgpr_count:     108
    .sgpr_spill_count: 215
    .symbol:         _Z6mk_fwd4Args.kd
    .uniform_work_group_size: 1
    .uses_dynamic_stack: false
    .vgpr_count:     256
    .vgpr_spill_count: 0
    .wavefront_size: 64
